# scan recurrences rewritten: VOP2 fmac chains, outputs reduced once per chunk by a transposing DPP butterfly
# speedup vs baseline: 1.0274x; 1.0172x over previous
.LBB0_1234:
	s_and_b32 s0, s13, 1
	s_mov_b64 s[2:3], -1
	s_and_b64 vcc, exec, s[10:11]
	s_cbranch_vccz .LBB0_1248
	s_mul_i32 s1, s0, 0x9900
	s_add_i32 s1, s1, 0
	s_and_b64 vcc, exec, s[48:49]
	s_cbranch_vccz .LBB0_1238
	s_andn2_b64 vcc, exec, s[44:45]
	s_cbranch_vccnz .LBB0_1796
	v_add_u32_e32 v0, s1, v121
	v_lshl_add_u32 v62, v120, 2, s1
	v_mov_b32_e32 v63, s1
	ds_read_b128 v[64:67], v0 offset:21504
	ds_read_b128 v[68:71], v0 offset:21520
	ds_read_b64 v[98:99], v63 offset:22592
	ds_read_b64 v[96:97], v62 offset:22528
	ds_read_b128 v[72:75], v0 offset:22016
	ds_read_b128 v[76:79], v0 offset:22032
	ds_read_b128 v[80:83], v0 offset:22608
	ds_read_b128 v[84:87], v0 offset:22624
	ds_read_b64 v[102:103], v63 offset:23696
	ds_read_b64 v[100:101], v62 offset:23632
	ds_read_b128 v[88:91], v0 offset:23120
	ds_read_b128 v[92:95], v0 offset:23136
	s_waitcnt lgkmcnt(6)
	v_mul_f32_e64 v160, -v99, v98
	v_mul_f32_e32 v161, v98, v96
	v_mul_f32_e32 v162, v98, v97
	v_mul_f32_e32 v156, v26, v64
	v_mul_f32_e32 v157, v34, v64
	v_fmac_f32_e32 v156, v27, v65
	v_fmac_f32_e32 v157, v35, v65
	v_fmac_f32_e32 v156, v28, v66
	v_fmac_f32_e32 v157, v36, v66
	v_fmac_f32_e32 v156, v29, v67
	v_fmac_f32_e32 v157, v37, v67
	v_fmac_f32_e32 v156, v30, v68
	v_fmac_f32_e32 v157, v38, v68
	v_fmac_f32_e32 v156, v31, v69
	v_fmac_f32_e32 v157, v39, v69
	v_fmac_f32_e32 v156, v32, v70
	v_fmac_f32_e32 v157, v40, v70
	v_fmac_f32_e32 v156, v33, v71
	v_fmac_f32_e32 v157, v41, v71
	v_mul_f32_e32 v26, v99, v26
	v_mul_f32_e32 v34, v99, v34
	v_add_f32_dpp v156, v156, v156 quad_perm:[1,0,3,2] row_mask:0xf bank_mask:0xf bound_ctrl:1
	v_add_f32_dpp v157, v157, v157 quad_perm:[1,0,3,2] row_mask:0xf bank_mask:0xf bound_ctrl:1
	v_mul_f32_e32 v27, v99, v27
	v_mul_f32_e32 v35, v99, v35
	v_mul_f32_e32 v28, v99, v28
	v_mul_f32_e32 v36, v99, v36
	v_add_f32_dpp v156, v156, v156 quad_perm:[2,3,0,1] row_mask:0xf bank_mask:0xf bound_ctrl:1
	v_add_f32_dpp v157, v157, v157 quad_perm:[2,3,0,1] row_mask:0xf bank_mask:0xf bound_ctrl:1
	v_mul_f32_e32 v29, v99, v29
	v_mul_f32_e32 v37, v99, v37
	v_mul_f32_e32 v30, v99, v30
	v_mul_f32_e32 v38, v99, v38
	v_add_f32_dpp v156, v156, v156 row_half_mirror row_mask:0xf bank_mask:0xf bound_ctrl:1
	v_add_f32_dpp v157, v157, v157 row_half_mirror row_mask:0xf bank_mask:0xf bound_ctrl:1
	v_mul_f32_e32 v31, v99, v31
	v_mul_f32_e32 v39, v99, v39
	v_mul_f32_e32 v32, v99, v32
	v_mul_f32_e32 v40, v99, v40
	v_add_f32_dpp v156, v156, v156 row_ror:8 row_mask:0xf bank_mask:0xf bound_ctrl:1
	v_add_f32_dpp v157, v157, v157 row_ror:8 row_mask:0xf bank_mask:0xf bound_ctrl:1
	v_mul_f32_e32 v33, v99, v33
	v_mul_f32_e32 v41, v99, v41
	v_fmac_f32_e32 v161, v160, v156
	v_fmac_f32_e32 v162, v160, v157
	v_fmac_f32_e32 v26, v64, v161
	v_fmac_f32_e32 v34, v64, v162
	v_fmac_f32_e32 v27, v65, v161
	v_fmac_f32_e32 v35, v65, v162
	v_fmac_f32_e32 v28, v66, v161
	v_fmac_f32_e32 v36, v66, v162
	v_fmac_f32_e32 v29, v67, v161
	v_fmac_f32_e32 v37, v67, v162
	v_fmac_f32_e32 v30, v68, v161
	v_fmac_f32_e32 v38, v68, v162
	v_fmac_f32_e32 v31, v69, v161
	v_fmac_f32_e32 v39, v69, v162
	v_fmac_f32_e32 v32, v70, v161
	v_fmac_f32_e32 v40, v70, v162
	v_fmac_f32_e32 v33, v71, v161
	v_fmac_f32_e32 v41, v71, v162
	ds_read_b128 v[64:67], v0 offset:23712
	ds_read_b128 v[68:71], v0 offset:23728
	ds_read_b64 v[98:99], v63 offset:24800
	ds_read_b64 v[96:97], v62 offset:24736
	ds_read_b128 v[148:151], v0 offset:24224
	ds_read_b128 v[152:155], v0 offset:24240
	s_waitcnt lgkmcnt(6)
	v_mul_f32_e64 v160, -v103, v102
	v_mul_f32_e32 v161, v102, v100
	v_mul_f32_e32 v162, v102, v101
	v_mul_f32_e32 v156, v26, v80
	v_mul_f32_e32 v157, v34, v80
	v_mul_f32_e32 v170, v26, v72
	v_mul_f32_e32 v186, v34, v72
	v_fmac_f32_e32 v156, v27, v81
	v_fmac_f32_e32 v157, v35, v81
	v_fmac_f32_e32 v170, v27, v73
	v_fmac_f32_e32 v186, v35, v73
	v_fmac_f32_e32 v156, v28, v82
	v_fmac_f32_e32 v157, v36, v82
	v_fmac_f32_e32 v170, v28, v74
	v_fmac_f32_e32 v186, v36, v74
	v_fmac_f32_e32 v156, v29, v83
	v_fmac_f32_e32 v157, v37, v83
	v_fmac_f32_e32 v170, v29, v75
	v_fmac_f32_e32 v186, v37, v75
	v_fmac_f32_e32 v156, v30, v84
	v_fmac_f32_e32 v157, v38, v84
	v_fmac_f32_e32 v170, v30, v76
	v_fmac_f32_e32 v186, v38, v76
	v_fmac_f32_e32 v156, v31, v85
	v_fmac_f32_e32 v157, v39, v85
	v_fmac_f32_e32 v170, v31, v77
	v_fmac_f32_e32 v186, v39, v77
	v_fmac_f32_e32 v156, v32, v86
	v_fmac_f32_e32 v157, v40, v86
	v_fmac_f32_e32 v170, v32, v78
	v_fmac_f32_e32 v186, v40, v78
	v_fmac_f32_e32 v156, v33, v87
	v_fmac_f32_e32 v157, v41, v87
	v_fmac_f32_e32 v170, v33, v79
	v_fmac_f32_e32 v186, v41, v79
	v_mul_f32_e32 v26, v103, v26
	v_mul_f32_e32 v34, v103, v34
	v_add_f32_dpp v156, v156, v156 quad_perm:[1,0,3,2] row_mask:0xf bank_mask:0xf bound_ctrl:1
	v_add_f32_dpp v157, v157, v157 quad_perm:[1,0,3,2] row_mask:0xf bank_mask:0xf bound_ctrl:1
	v_mul_f32_e32 v27, v103, v27
	v_mul_f32_e32 v35, v103, v35
	v_mul_f32_e32 v28, v103, v28
	v_mul_f32_e32 v36, v103, v36
	v_add_f32_dpp v156, v156, v156 quad_perm:[2,3,0,1] row_mask:0xf bank_mask:0xf bound_ctrl:1
	v_add_f32_dpp v157, v157, v157 quad_perm:[2,3,0,1] row_mask:0xf bank_mask:0xf bound_ctrl:1
	v_mul_f32_e32 v29, v103, v29
	v_mul_f32_e32 v37, v103, v37
	v_mul_f32_e32 v30, v103, v30
	v_mul_f32_e32 v38, v103, v38
	v_add_f32_dpp v156, v156, v156 row_half_mirror row_mask:0xf bank_mask:0xf bound_ctrl:1
	v_add_f32_dpp v157, v157, v157 row_half_mirror row_mask:0xf bank_mask:0xf bound_ctrl:1
	v_mul_f32_e32 v31, v103, v31
	v_mul_f32_e32 v39, v103, v39
	v_mul_f32_e32 v32, v103, v32
	v_mul_f32_e32 v40, v103, v40
	v_add_f32_dpp v156, v156, v156 row_ror:8 row_mask:0xf bank_mask:0xf bound_ctrl:1
	v_add_f32_dpp v157, v157, v157 row_ror:8 row_mask:0xf bank_mask:0xf bound_ctrl:1
	v_mul_f32_e32 v33, v103, v33
	v_mul_f32_e32 v41, v103, v41
	v_fmac_f32_e32 v161, v160, v156
	v_fmac_f32_e32 v162, v160, v157
	v_fmac_f32_e32 v26, v80, v161
	v_fmac_f32_e32 v34, v80, v162
	v_fmac_f32_e32 v27, v81, v161
	v_fmac_f32_e32 v35, v81, v162
	v_fmac_f32_e32 v28, v82, v161
	v_fmac_f32_e32 v36, v82, v162
	v_fmac_f32_e32 v29, v83, v161
	v_fmac_f32_e32 v37, v83, v162
	v_fmac_f32_e32 v30, v84, v161
	v_fmac_f32_e32 v38, v84, v162
	v_fmac_f32_e32 v31, v85, v161
	v_fmac_f32_e32 v39, v85, v162
	v_fmac_f32_e32 v32, v86, v161
	v_fmac_f32_e32 v40, v86, v162
	v_fmac_f32_e32 v33, v87, v161
	v_fmac_f32_e32 v41, v87, v162
	ds_read_b128 v[80:83], v0 offset:24816
	ds_read_b128 v[84:87], v0 offset:24832
	ds_read_b64 v[102:103], v63 offset:25904
	ds_read_b64 v[100:101], v62 offset:25840
	ds_read_b128 v[72:75], v0 offset:25328
	ds_read_b128 v[76:79], v0 offset:25344
	s_waitcnt lgkmcnt(6)
	v_mul_f32_e64 v160, -v99, v98
	v_mul_f32_e32 v161, v98, v96
	v_mul_f32_e32 v162, v98, v97
	v_mul_f32_e32 v156, v26, v64
	v_mul_f32_e32 v157, v34, v64
	v_mul_f32_e32 v171, v26, v88
	v_mul_f32_e32 v187, v34, v88
	v_fmac_f32_e32 v156, v27, v65
	v_fmac_f32_e32 v157, v35, v65
	v_fmac_f32_e32 v171, v27, v89
	v_fmac_f32_e32 v187, v35, v89
	v_fmac_f32_e32 v156, v28, v66
	v_fmac_f32_e32 v157, v36, v66
	v_fmac_f32_e32 v171, v28, v90
	v_fmac_f32_e32 v187, v36, v90
	v_fmac_f32_e32 v156, v29, v67
	v_fmac_f32_e32 v157, v37, v67
	v_fmac_f32_e32 v171, v29, v91
	v_fmac_f32_e32 v187, v37, v91
	v_fmac_f32_e32 v156, v30, v68
	v_fmac_f32_e32 v157, v38, v68
	v_fmac_f32_e32 v171, v30, v92
	v_fmac_f32_e32 v187, v38, v92
	v_fmac_f32_e32 v156, v31, v69
	v_fmac_f32_e32 v157, v39, v69
	v_fmac_f32_e32 v171, v31, v93
	v_fmac_f32_e32 v187, v39, v93
	v_fmac_f32_e32 v156, v32, v70
	v_fmac_f32_e32 v157, v40, v70
	v_fmac_f32_e32 v171, v32, v94
	v_fmac_f32_e32 v187, v40, v94
	v_fmac_f32_e32 v156, v33, v71
	v_fmac_f32_e32 v157, v41, v71
	v_fmac_f32_e32 v171, v33, v95
	v_fmac_f32_e32 v187, v41, v95
	v_mul_f32_e32 v26, v99, v26
	v_mul_f32_e32 v34, v99, v34
	v_add_f32_dpp v156, v156, v156 quad_perm:[1,0,3,2] row_mask:0xf bank_mask:0xf bound_ctrl:1
	v_add_f32_dpp v157, v157, v157 quad_perm:[1,0,3,2] row_mask:0xf bank_mask:0xf bound_ctrl:1
	v_mul_f32_e32 v27, v99, v27
	v_mul_f32_e32 v35, v99, v35
	v_mul_f32_e32 v28, v99, v28
	v_mul_f32_e32 v36, v99, v36
	v_add_f32_dpp v156, v156, v156 quad_perm:[2,3,0,1] row_mask:0xf bank_mask:0xf bound_ctrl:1
	v_add_f32_dpp v157, v157, v157 quad_perm:[2,3,0,1] row_mask:0xf bank_mask:0xf bound_ctrl:1
	v_mul_f32_e32 v29, v99, v29
	v_mul_f32_e32 v37, v99, v37
	v_mul_f32_e32 v30, v99, v30
	v_mul_f32_e32 v38, v99, v38
	v_add_f32_dpp v156, v156, v156 row_half_mirror row_mask:0xf bank_mask:0xf bound_ctrl:1
	v_add_f32_dpp v157, v157, v157 row_half_mirror row_mask:0xf bank_mask:0xf bound_ctrl:1
	v_mul_f32_e32 v31, v99, v31
	v_mul_f32_e32 v39, v99, v39
	v_mul_f32_e32 v32, v99, v32
	v_mul_f32_e32 v40, v99, v40
	v_add_f32_dpp v156, v156, v156 row_ror:8 row_mask:0xf bank_mask:0xf bound_ctrl:1
	v_add_f32_dpp v157, v157, v157 row_ror:8 row_mask:0xf bank_mask:0xf bound_ctrl:1
	v_mul_f32_e32 v33, v99, v33
	v_mul_f32_e32 v41, v99, v41
	v_fmac_f32_e32 v161, v160, v156
	v_fmac_f32_e32 v162, v160, v157
	v_fmac_f32_e32 v26, v64, v161
	v_fmac_f32_e32 v34, v64, v162
	v_fmac_f32_e32 v27, v65, v161
	v_fmac_f32_e32 v35, v65, v162
	v_fmac_f32_e32 v28, v66, v161
	v_fmac_f32_e32 v36, v66, v162
	v_fmac_f32_e32 v29, v67, v161
	v_fmac_f32_e32 v37, v67, v162
	v_fmac_f32_e32 v30, v68, v161
	v_fmac_f32_e32 v38, v68, v162
	v_fmac_f32_e32 v31, v69, v161
	v_fmac_f32_e32 v39, v69, v162
	v_fmac_f32_e32 v32, v70, v161
	v_fmac_f32_e32 v40, v70, v162
	v_fmac_f32_e32 v33, v71, v161
	v_fmac_f32_e32 v41, v71, v162
	ds_read_b128 v[64:67], v0 offset:25920
	ds_read_b128 v[68:71], v0 offset:25936
	ds_read_b64 v[98:99], v63 offset:27008
	ds_read_b64 v[96:97], v62 offset:26944
	ds_read_b128 v[88:91], v0 offset:26432
	ds_read_b128 v[92:95], v0 offset:26448
	s_waitcnt lgkmcnt(6)
	v_mul_f32_e64 v160, -v103, v102
	v_mul_f32_e32 v161, v102, v100
	v_mul_f32_e32 v162, v102, v101
	v_mul_f32_e32 v156, v26, v80
	v_mul_f32_e32 v157, v34, v80
	v_mul_f32_e32 v172, v26, v148
	v_mul_f32_e32 v188, v34, v148
	v_fmac_f32_e32 v156, v27, v81
	v_fmac_f32_e32 v157, v35, v81
	v_fmac_f32_e32 v172, v27, v149
	v_fmac_f32_e32 v188, v35, v149
	v_fmac_f32_e32 v156, v28, v82
	v_fmac_f32_e32 v157, v36, v82
	v_fmac_f32_e32 v172, v28, v150
	v_fmac_f32_e32 v188, v36, v150
	v_fmac_f32_e32 v156, v29, v83
	v_fmac_f32_e32 v157, v37, v83
	v_fmac_f32_e32 v172, v29, v151
	v_fmac_f32_e32 v188, v37, v151
	v_fmac_f32_e32 v156, v30, v84
	v_fmac_f32_e32 v157, v38, v84
	v_fmac_f32_e32 v172, v30, v152
	v_fmac_f32_e32 v188, v38, v152
	v_fmac_f32_e32 v156, v31, v85
	v_fmac_f32_e32 v157, v39, v85
	v_fmac_f32_e32 v172, v31, v153
	v_fmac_f32_e32 v188, v39, v153
	v_fmac_f32_e32 v156, v32, v86
	v_fmac_f32_e32 v157, v40, v86
	v_fmac_f32_e32 v172, v32, v154
	v_fmac_f32_e32 v188, v40, v154
	v_fmac_f32_e32 v156, v33, v87
	v_fmac_f32_e32 v157, v41, v87
	v_fmac_f32_e32 v172, v33, v155
	v_fmac_f32_e32 v188, v41, v155
	v_mul_f32_e32 v26, v103, v26
	v_mul_f32_e32 v34, v103, v34
	v_add_f32_dpp v156, v156, v156 quad_perm:[1,0,3,2] row_mask:0xf bank_mask:0xf bound_ctrl:1
	v_add_f32_dpp v157, v157, v157 quad_perm:[1,0,3,2] row_mask:0xf bank_mask:0xf bound_ctrl:1
	v_mul_f32_e32 v27, v103, v27
	v_mul_f32_e32 v35, v103, v35
	v_mul_f32_e32 v28, v103, v28
	v_mul_f32_e32 v36, v103, v36
	v_add_f32_dpp v156, v156, v156 quad_perm:[2,3,0,1] row_mask:0xf bank_mask:0xf bound_ctrl:1
	v_add_f32_dpp v157, v157, v157 quad_perm:[2,3,0,1] row_mask:0xf bank_mask:0xf bound_ctrl:1
	v_mul_f32_e32 v29, v103, v29
	v_mul_f32_e32 v37, v103, v37
	v_mul_f32_e32 v30, v103, v30
	v_mul_f32_e32 v38, v103, v38
	v_add_f32_dpp v156, v156, v156 row_half_mirror row_mask:0xf bank_mask:0xf bound_ctrl:1
	v_add_f32_dpp v157, v157, v157 row_half_mirror row_mask:0xf bank_mask:0xf bound_ctrl:1
	v_mul_f32_e32 v31, v103, v31
	v_mul_f32_e32 v39, v103, v39
	v_mul_f32_e32 v32, v103, v32
	v_mul_f32_e32 v40, v103, v40
	v_add_f32_dpp v156, v156, v156 row_ror:8 row_mask:0xf bank_mask:0xf bound_ctrl:1
	v_add_f32_dpp v157, v157, v157 row_ror:8 row_mask:0xf bank_mask:0xf bound_ctrl:1
	v_mul_f32_e32 v33, v103, v33
	v_mul_f32_e32 v41, v103, v41
	v_fmac_f32_e32 v161, v160, v156
	v_fmac_f32_e32 v162, v160, v157
	v_fmac_f32_e32 v26, v80, v161
	v_fmac_f32_e32 v34, v80, v162
	v_fmac_f32_e32 v27, v81, v161
	v_fmac_f32_e32 v35, v81, v162
	v_fmac_f32_e32 v28, v82, v161
	v_fmac_f32_e32 v36, v82, v162
	v_fmac_f32_e32 v29, v83, v161
	v_fmac_f32_e32 v37, v83, v162
	v_fmac_f32_e32 v30, v84, v161
	v_fmac_f32_e32 v38, v84, v162
	v_fmac_f32_e32 v31, v85, v161
	v_fmac_f32_e32 v39, v85, v162
	v_fmac_f32_e32 v32, v86, v161
	v_fmac_f32_e32 v40, v86, v162
	v_fmac_f32_e32 v33, v87, v161
	v_fmac_f32_e32 v41, v87, v162
	ds_read_b128 v[80:83], v0 offset:27024
	ds_read_b128 v[84:87], v0 offset:27040
	ds_read_b64 v[102:103], v63 offset:28112
	ds_read_b64 v[100:101], v62 offset:28048
	ds_read_b128 v[148:151], v0 offset:27536
	ds_read_b128 v[152:155], v0 offset:27552
	s_waitcnt lgkmcnt(6)
	v_mul_f32_e64 v160, -v99, v98
	v_mul_f32_e32 v161, v98, v96
	v_mul_f32_e32 v162, v98, v97
	v_mul_f32_e32 v156, v26, v64
	v_mul_f32_e32 v157, v34, v64
	v_mul_f32_e32 v173, v26, v72
	v_mul_f32_e32 v189, v34, v72
	v_fmac_f32_e32 v156, v27, v65
	v_fmac_f32_e32 v157, v35, v65
	v_fmac_f32_e32 v173, v27, v73
	v_fmac_f32_e32 v189, v35, v73
	v_fmac_f32_e32 v156, v28, v66
	v_fmac_f32_e32 v157, v36, v66
	v_fmac_f32_e32 v173, v28, v74
	v_fmac_f32_e32 v189, v36, v74
	v_fmac_f32_e32 v156, v29, v67
	v_fmac_f32_e32 v157, v37, v67
	v_fmac_f32_e32 v173, v29, v75
	v_fmac_f32_e32 v189, v37, v75
	v_fmac_f32_e32 v156, v30, v68
	v_fmac_f32_e32 v157, v38, v68
	v_fmac_f32_e32 v173, v30, v76
	v_fmac_f32_e32 v189, v38, v76
	v_fmac_f32_e32 v156, v31, v69
	v_fmac_f32_e32 v157, v39, v69
	v_fmac_f32_e32 v173, v31, v77
	v_fmac_f32_e32 v189, v39, v77
	v_fmac_f32_e32 v156, v32, v70
	v_fmac_f32_e32 v157, v40, v70
	v_fmac_f32_e32 v173, v32, v78
	v_fmac_f32_e32 v189, v40, v78
	v_fmac_f32_e32 v156, v33, v71
	v_fmac_f32_e32 v157, v41, v71
	v_fmac_f32_e32 v173, v33, v79
	v_fmac_f32_e32 v189, v41, v79
	v_mul_f32_e32 v26, v99, v26
	v_mul_f32_e32 v34, v99, v34
	v_add_f32_dpp v156, v156, v156 quad_perm:[1,0,3,2] row_mask:0xf bank_mask:0xf bound_ctrl:1
	v_add_f32_dpp v157, v157, v157 quad_perm:[1,0,3,2] row_mask:0xf bank_mask:0xf bound_ctrl:1
	v_mul_f32_e32 v27, v99, v27
	v_mul_f32_e32 v35, v99, v35
	v_mul_f32_e32 v28, v99, v28
	v_mul_f32_e32 v36, v99, v36
	v_add_f32_dpp v156, v156, v156 quad_perm:[2,3,0,1] row_mask:0xf bank_mask:0xf bound_ctrl:1
	v_add_f32_dpp v157, v157, v157 quad_perm:[2,3,0,1] row_mask:0xf bank_mask:0xf bound_ctrl:1
	v_mul_f32_e32 v29, v99, v29
	v_mul_f32_e32 v37, v99, v37
	v_mul_f32_e32 v30, v99, v30
	v_mul_f32_e32 v38, v99, v38
	v_add_f32_dpp v156, v156, v156 row_half_mirror row_mask:0xf bank_mask:0xf bound_ctrl:1
	v_add_f32_dpp v157, v157, v157 row_half_mirror row_mask:0xf bank_mask:0xf bound_ctrl:1
	v_mul_f32_e32 v31, v99, v31
	v_mul_f32_e32 v39, v99, v39
	v_mul_f32_e32 v32, v99, v32
	v_mul_f32_e32 v40, v99, v40
	v_add_f32_dpp v156, v156, v156 row_ror:8 row_mask:0xf bank_mask:0xf bound_ctrl:1
	v_add_f32_dpp v157, v157, v157 row_ror:8 row_mask:0xf bank_mask:0xf bound_ctrl:1
	v_mul_f32_e32 v33, v99, v33
	v_mul_f32_e32 v41, v99, v41
	v_fmac_f32_e32 v161, v160, v156
	v_fmac_f32_e32 v162, v160, v157
	v_fmac_f32_e32 v26, v64, v161
	v_fmac_f32_e32 v34, v64, v162
	v_fmac_f32_e32 v27, v65, v161
	v_fmac_f32_e32 v35, v65, v162
	v_fmac_f32_e32 v28, v66, v161
	v_fmac_f32_e32 v36, v66, v162
	v_fmac_f32_e32 v29, v67, v161
	v_fmac_f32_e32 v37, v67, v162
	v_fmac_f32_e32 v30, v68, v161
	v_fmac_f32_e32 v38, v68, v162
	v_fmac_f32_e32 v31, v69, v161
	v_fmac_f32_e32 v39, v69, v162
	v_fmac_f32_e32 v32, v70, v161
	v_fmac_f32_e32 v40, v70, v162
	v_fmac_f32_e32 v33, v71, v161
	v_fmac_f32_e32 v41, v71, v162
	ds_read_b128 v[64:67], v0 offset:28128
	ds_read_b128 v[68:71], v0 offset:28144
	ds_read_b64 v[98:99], v63 offset:29216
	ds_read_b64 v[96:97], v62 offset:29152
	ds_read_b128 v[72:75], v0 offset:28640
	ds_read_b128 v[76:79], v0 offset:28656
	s_waitcnt lgkmcnt(6)
	v_mul_f32_e64 v160, -v103, v102
	v_mul_f32_e32 v161, v102, v100
	v_mul_f32_e32 v162, v102, v101
	v_mul_f32_e32 v156, v26, v80
	v_mul_f32_e32 v157, v34, v80
	v_mul_f32_e32 v174, v26, v88
	v_mul_f32_e32 v190, v34, v88
	v_fmac_f32_e32 v156, v27, v81
	v_fmac_f32_e32 v157, v35, v81
	v_fmac_f32_e32 v174, v27, v89
	v_fmac_f32_e32 v190, v35, v89
	v_fmac_f32_e32 v156, v28, v82
	v_fmac_f32_e32 v157, v36, v82
	v_fmac_f32_e32 v174, v28, v90
	v_fmac_f32_e32 v190, v36, v90
	v_fmac_f32_e32 v156, v29, v83
	v_fmac_f32_e32 v157, v37, v83
	v_fmac_f32_e32 v174, v29, v91
	v_fmac_f32_e32 v190, v37, v91
	v_fmac_f32_e32 v156, v30, v84
	v_fmac_f32_e32 v157, v38, v84
	v_fmac_f32_e32 v174, v30, v92
	v_fmac_f32_e32 v190, v38, v92
	v_fmac_f32_e32 v156, v31, v85
	v_fmac_f32_e32 v157, v39, v85
	v_fmac_f32_e32 v174, v31, v93
	v_fmac_f32_e32 v190, v39, v93
	v_fmac_f32_e32 v156, v32, v86
	v_fmac_f32_e32 v157, v40, v86
	v_fmac_f32_e32 v174, v32, v94
	v_fmac_f32_e32 v190, v40, v94
	v_fmac_f32_e32 v156, v33, v87
	v_fmac_f32_e32 v157, v41, v87
	v_fmac_f32_e32 v174, v33, v95
	v_fmac_f32_e32 v190, v41, v95
	v_mul_f32_e32 v26, v103, v26
	v_mul_f32_e32 v34, v103, v34
	v_add_f32_dpp v156, v156, v156 quad_perm:[1,0,3,2] row_mask:0xf bank_mask:0xf bound_ctrl:1
	v_add_f32_dpp v157, v157, v157 quad_perm:[1,0,3,2] row_mask:0xf bank_mask:0xf bound_ctrl:1
	v_mul_f32_e32 v27, v103, v27
	v_mul_f32_e32 v35, v103, v35
	v_mul_f32_e32 v28, v103, v28
	v_mul_f32_e32 v36, v103, v36
	v_add_f32_dpp v156, v156, v156 quad_perm:[2,3,0,1] row_mask:0xf bank_mask:0xf bound_ctrl:1
	v_add_f32_dpp v157, v157, v157 quad_perm:[2,3,0,1] row_mask:0xf bank_mask:0xf bound_ctrl:1
	v_mul_f32_e32 v29, v103, v29
	v_mul_f32_e32 v37, v103, v37
	v_mul_f32_e32 v30, v103, v30
	v_mul_f32_e32 v38, v103, v38
	v_add_f32_dpp v156, v156, v156 row_half_mirror row_mask:0xf bank_mask:0xf bound_ctrl:1
	v_add_f32_dpp v157, v157, v157 row_half_mirror row_mask:0xf bank_mask:0xf bound_ctrl:1
	v_mul_f32_e32 v31, v103, v31
	v_mul_f32_e32 v39, v103, v39
	v_mul_f32_e32 v32, v103, v32
	v_mul_f32_e32 v40, v103, v40
	v_add_f32_dpp v156, v156, v156 row_ror:8 row_mask:0xf bank_mask:0xf bound_ctrl:1
	v_add_f32_dpp v157, v157, v157 row_ror:8 row_mask:0xf bank_mask:0xf bound_ctrl:1
	v_mul_f32_e32 v33, v103, v33
	v_mul_f32_e32 v41, v103, v41
	v_fmac_f32_e32 v161, v160, v156
	v_fmac_f32_e32 v162, v160, v157
	v_fmac_f32_e32 v26, v80, v161
	v_fmac_f32_e32 v34, v80, v162
	v_fmac_f32_e32 v27, v81, v161
	v_fmac_f32_e32 v35, v81, v162
	v_fmac_f32_e32 v28, v82, v161
	v_fmac_f32_e32 v36, v82, v162
	v_fmac_f32_e32 v29, v83, v161
	v_fmac_f32_e32 v37, v83, v162
	v_fmac_f32_e32 v30, v84, v161
	v_fmac_f32_e32 v38, v84, v162
	v_fmac_f32_e32 v31, v85, v161
	v_fmac_f32_e32 v39, v85, v162
	v_fmac_f32_e32 v32, v86, v161
	v_fmac_f32_e32 v40, v86, v162
	v_fmac_f32_e32 v33, v87, v161
	v_fmac_f32_e32 v41, v87, v162
	ds_read_b128 v[80:83], v0 offset:29232
	ds_read_b128 v[84:87], v0 offset:29248
	ds_read_b64 v[102:103], v63 offset:30320
	ds_read_b64 v[100:101], v62 offset:30256
	ds_read_b128 v[88:91], v0 offset:29744
	ds_read_b128 v[92:95], v0 offset:29760
	s_waitcnt lgkmcnt(6)
	v_mul_f32_e64 v160, -v99, v98
	v_mul_f32_e32 v161, v98, v96
	v_mul_f32_e32 v162, v98, v97
	v_mul_f32_e32 v156, v26, v64
	v_mul_f32_e32 v157, v34, v64
	v_mul_f32_e32 v175, v26, v148
	v_mul_f32_e32 v191, v34, v148
	v_fmac_f32_e32 v156, v27, v65
	v_fmac_f32_e32 v157, v35, v65
	v_fmac_f32_e32 v175, v27, v149
	v_fmac_f32_e32 v191, v35, v149
	v_fmac_f32_e32 v156, v28, v66
	v_fmac_f32_e32 v157, v36, v66
	v_fmac_f32_e32 v175, v28, v150
	v_fmac_f32_e32 v191, v36, v150
	v_fmac_f32_e32 v156, v29, v67
	v_fmac_f32_e32 v157, v37, v67
	v_fmac_f32_e32 v175, v29, v151
	v_fmac_f32_e32 v191, v37, v151
	v_fmac_f32_e32 v156, v30, v68
	v_fmac_f32_e32 v157, v38, v68
	v_fmac_f32_e32 v175, v30, v152
	v_fmac_f32_e32 v191, v38, v152
	v_fmac_f32_e32 v156, v31, v69
	v_fmac_f32_e32 v157, v39, v69
	v_fmac_f32_e32 v175, v31, v153
	v_fmac_f32_e32 v191, v39, v153
	v_fmac_f32_e32 v156, v32, v70
	v_fmac_f32_e32 v157, v40, v70
	v_fmac_f32_e32 v175, v32, v154
	v_fmac_f32_e32 v191, v40, v154
	v_fmac_f32_e32 v156, v33, v71
	v_fmac_f32_e32 v157, v41, v71
	v_fmac_f32_e32 v175, v33, v155
	v_fmac_f32_e32 v191, v41, v155
	v_mul_f32_e32 v26, v99, v26
	v_mul_f32_e32 v34, v99, v34
	v_add_f32_dpp v156, v156, v156 quad_perm:[1,0,3,2] row_mask:0xf bank_mask:0xf bound_ctrl:1
	v_add_f32_dpp v157, v157, v157 quad_perm:[1,0,3,2] row_mask:0xf bank_mask:0xf bound_ctrl:1
	v_mul_f32_e32 v27, v99, v27
	v_mul_f32_e32 v35, v99, v35
	v_mul_f32_e32 v28, v99, v28
	v_mul_f32_e32 v36, v99, v36
	v_add_f32_dpp v156, v156, v156 quad_perm:[2,3,0,1] row_mask:0xf bank_mask:0xf bound_ctrl:1
	v_add_f32_dpp v157, v157, v157 quad_perm:[2,3,0,1] row_mask:0xf bank_mask:0xf bound_ctrl:1
	v_mul_f32_e32 v29, v99, v29
	v_mul_f32_e32 v37, v99, v37
	v_mul_f32_e32 v30, v99, v30
	v_mul_f32_e32 v38, v99, v38
	v_add_f32_dpp v156, v156, v156 row_half_mirror row_mask:0xf bank_mask:0xf bound_ctrl:1
	v_add_f32_dpp v157, v157, v157 row_half_mirror row_mask:0xf bank_mask:0xf bound_ctrl:1
	v_mul_f32_e32 v31, v99, v31
	v_mul_f32_e32 v39, v99, v39
	v_mul_f32_e32 v32, v99, v32
	v_mul_f32_e32 v40, v99, v40
	v_add_f32_dpp v156, v156, v156 row_ror:8 row_mask:0xf bank_mask:0xf bound_ctrl:1
	v_add_f32_dpp v157, v157, v157 row_ror:8 row_mask:0xf bank_mask:0xf bound_ctrl:1
	v_mul_f32_e32 v33, v99, v33
	v_mul_f32_e32 v41, v99, v41
	v_fmac_f32_e32 v161, v160, v156
	v_fmac_f32_e32 v162, v160, v157
	v_fmac_f32_e32 v26, v64, v161
	v_fmac_f32_e32 v34, v64, v162
	v_fmac_f32_e32 v27, v65, v161
	v_fmac_f32_e32 v35, v65, v162
	v_fmac_f32_e32 v28, v66, v161
	v_fmac_f32_e32 v36, v66, v162
	v_fmac_f32_e32 v29, v67, v161
	v_fmac_f32_e32 v37, v67, v162
	v_fmac_f32_e32 v30, v68, v161
	v_fmac_f32_e32 v38, v68, v162
	v_fmac_f32_e32 v31, v69, v161
	v_fmac_f32_e32 v39, v69, v162
	v_fmac_f32_e32 v32, v70, v161
	v_fmac_f32_e32 v40, v70, v162
	v_fmac_f32_e32 v33, v71, v161
	v_fmac_f32_e32 v41, v71, v162
	ds_read_b128 v[64:67], v0 offset:30336
	ds_read_b128 v[68:71], v0 offset:30352
	ds_read_b64 v[98:99], v63 offset:31424
	ds_read_b64 v[96:97], v62 offset:31360
	ds_read_b128 v[148:151], v0 offset:30848
	ds_read_b128 v[152:155], v0 offset:30864
	s_waitcnt lgkmcnt(6)
	v_mul_f32_e64 v160, -v103, v102
	v_mul_f32_e32 v161, v102, v100
	v_mul_f32_e32 v162, v102, v101
	v_mul_f32_e32 v156, v26, v80
	v_mul_f32_e32 v157, v34, v80
	v_mul_f32_e32 v176, v26, v72
	v_mul_f32_e32 v192, v34, v72
	v_fmac_f32_e32 v156, v27, v81
	v_fmac_f32_e32 v157, v35, v81
	v_fmac_f32_e32 v176, v27, v73
	v_fmac_f32_e32 v192, v35, v73
	v_fmac_f32_e32 v156, v28, v82
	v_fmac_f32_e32 v157, v36, v82
	v_fmac_f32_e32 v176, v28, v74
	v_fmac_f32_e32 v192, v36, v74
	v_fmac_f32_e32 v156, v29, v83
	v_fmac_f32_e32 v157, v37, v83
	v_fmac_f32_e32 v176, v29, v75
	v_fmac_f32_e32 v192, v37, v75
	v_fmac_f32_e32 v156, v30, v84
	v_fmac_f32_e32 v157, v38, v84
	v_fmac_f32_e32 v176, v30, v76
	v_fmac_f32_e32 v192, v38, v76
	v_fmac_f32_e32 v156, v31, v85
	v_fmac_f32_e32 v157, v39, v85
	v_fmac_f32_e32 v176, v31, v77
	v_fmac_f32_e32 v192, v39, v77
	v_fmac_f32_e32 v156, v32, v86
	v_fmac_f32_e32 v157, v40, v86
	v_fmac_f32_e32 v176, v32, v78
	v_fmac_f32_e32 v192, v40, v78
	v_fmac_f32_e32 v156, v33, v87
	v_fmac_f32_e32 v157, v41, v87
	v_fmac_f32_e32 v176, v33, v79
	v_fmac_f32_e32 v192, v41, v79
	v_mul_f32_e32 v26, v103, v26
	v_mul_f32_e32 v34, v103, v34
	v_add_f32_dpp v156, v156, v156 quad_perm:[1,0,3,2] row_mask:0xf bank_mask:0xf bound_ctrl:1
	v_add_f32_dpp v157, v157, v157 quad_perm:[1,0,3,2] row_mask:0xf bank_mask:0xf bound_ctrl:1
	v_mul_f32_e32 v27, v103, v27
	v_mul_f32_e32 v35, v103, v35
	v_mul_f32_e32 v28, v103, v28
	v_mul_f32_e32 v36, v103, v36
	v_add_f32_dpp v156, v156, v156 quad_perm:[2,3,0,1] row_mask:0xf bank_mask:0xf bound_ctrl:1
	v_add_f32_dpp v157, v157, v157 quad_perm:[2,3,0,1] row_mask:0xf bank_mask:0xf bound_ctrl:1
	v_mul_f32_e32 v29, v103, v29
	v_mul_f32_e32 v37, v103, v37
	v_mul_f32_e32 v30, v103, v30
	v_mul_f32_e32 v38, v103, v38
	v_add_f32_dpp v156, v156, v156 row_half_mirror row_mask:0xf bank_mask:0xf bound_ctrl:1
	v_add_f32_dpp v157, v157, v157 row_half_mirror row_mask:0xf bank_mask:0xf bound_ctrl:1
	v_mul_f32_e32 v31, v103, v31
	v_mul_f32_e32 v39, v103, v39
	v_mul_f32_e32 v32, v103, v32
	v_mul_f32_e32 v40, v103, v40
	v_add_f32_dpp v156, v156, v156 row_ror:8 row_mask:0xf bank_mask:0xf bound_ctrl:1
	v_add_f32_dpp v157, v157, v157 row_ror:8 row_mask:0xf bank_mask:0xf bound_ctrl:1
	v_mul_f32_e32 v33, v103, v33
	v_mul_f32_e32 v41, v103, v41
	v_fmac_f32_e32 v161, v160, v156
	v_fmac_f32_e32 v162, v160, v157
	v_fmac_f32_e32 v26, v80, v161
	v_fmac_f32_e32 v34, v80, v162
	v_fmac_f32_e32 v27, v81, v161
	v_fmac_f32_e32 v35, v81, v162
	v_fmac_f32_e32 v28, v82, v161
	v_fmac_f32_e32 v36, v82, v162
	v_fmac_f32_e32 v29, v83, v161
	v_fmac_f32_e32 v37, v83, v162
	v_fmac_f32_e32 v30, v84, v161
	v_fmac_f32_e32 v38, v84, v162
	v_fmac_f32_e32 v31, v85, v161
	v_fmac_f32_e32 v39, v85, v162
	v_fmac_f32_e32 v32, v86, v161
	v_fmac_f32_e32 v40, v86, v162
	v_fmac_f32_e32 v33, v87, v161
	v_fmac_f32_e32 v41, v87, v162
	ds_read_b128 v[80:83], v0 offset:31440
	ds_read_b128 v[84:87], v0 offset:31456
	ds_read_b64 v[102:103], v63 offset:32528
	ds_read_b64 v[100:101], v62 offset:32464
	ds_read_b128 v[72:75], v0 offset:31952
	ds_read_b128 v[76:79], v0 offset:31968
	s_waitcnt lgkmcnt(6)
	v_mul_f32_e64 v160, -v99, v98
	v_mul_f32_e32 v161, v98, v96
	v_mul_f32_e32 v162, v98, v97
	v_mul_f32_e32 v156, v26, v64
	v_mul_f32_e32 v157, v34, v64
	v_mul_f32_e32 v177, v26, v88
	v_mul_f32_e32 v193, v34, v88
	v_fmac_f32_e32 v156, v27, v65
	v_fmac_f32_e32 v157, v35, v65
	v_fmac_f32_e32 v177, v27, v89
	v_fmac_f32_e32 v193, v35, v89
	v_fmac_f32_e32 v156, v28, v66
	v_fmac_f32_e32 v157, v36, v66
	v_fmac_f32_e32 v177, v28, v90
	v_fmac_f32_e32 v193, v36, v90
	v_fmac_f32_e32 v156, v29, v67
	v_fmac_f32_e32 v157, v37, v67
	v_fmac_f32_e32 v177, v29, v91
	v_fmac_f32_e32 v193, v37, v91
	v_fmac_f32_e32 v156, v30, v68
	v_fmac_f32_e32 v157, v38, v68
	v_fmac_f32_e32 v177, v30, v92
	v_fmac_f32_e32 v193, v38, v92
	v_fmac_f32_e32 v156, v31, v69
	v_fmac_f32_e32 v157, v39, v69
	v_fmac_f32_e32 v177, v31, v93
	v_fmac_f32_e32 v193, v39, v93
	v_fmac_f32_e32 v156, v32, v70
	v_fmac_f32_e32 v157, v40, v70
	v_fmac_f32_e32 v177, v32, v94
	v_fmac_f32_e32 v193, v40, v94
	v_fmac_f32_e32 v156, v33, v71
	v_fmac_f32_e32 v157, v41, v71
	v_fmac_f32_e32 v177, v33, v95
	v_fmac_f32_e32 v193, v41, v95
	v_mul_f32_e32 v26, v99, v26
	v_mul_f32_e32 v34, v99, v34
	v_add_f32_dpp v156, v156, v156 quad_perm:[1,0,3,2] row_mask:0xf bank_mask:0xf bound_ctrl:1
	v_add_f32_dpp v157, v157, v157 quad_perm:[1,0,3,2] row_mask:0xf bank_mask:0xf bound_ctrl:1
	v_mul_f32_e32 v27, v99, v27
	v_mul_f32_e32 v35, v99, v35
	v_mul_f32_e32 v28, v99, v28
	v_mul_f32_e32 v36, v99, v36
	v_add_f32_dpp v156, v156, v156 quad_perm:[2,3,0,1] row_mask:0xf bank_mask:0xf bound_ctrl:1
	v_add_f32_dpp v157, v157, v157 quad_perm:[2,3,0,1] row_mask:0xf bank_mask:0xf bound_ctrl:1
	v_mul_f32_e32 v29, v99, v29
	v_mul_f32_e32 v37, v99, v37
	v_mul_f32_e32 v30, v99, v30
	v_mul_f32_e32 v38, v99, v38
	v_add_f32_dpp v156, v156, v156 row_half_mirror row_mask:0xf bank_mask:0xf bound_ctrl:1
	v_add_f32_dpp v157, v157, v157 row_half_mirror row_mask:0xf bank_mask:0xf bound_ctrl:1
	v_mul_f32_e32 v31, v99, v31
	v_mul_f32_e32 v39, v99, v39
	v_mul_f32_e32 v32, v99, v32
	v_mul_f32_e32 v40, v99, v40
	v_add_f32_dpp v156, v156, v156 row_ror:8 row_mask:0xf bank_mask:0xf bound_ctrl:1
	v_add_f32_dpp v157, v157, v157 row_ror:8 row_mask:0xf bank_mask:0xf bound_ctrl:1
	v_mul_f32_e32 v33, v99, v33
	v_mul_f32_e32 v41, v99, v41
	v_fmac_f32_e32 v161, v160, v156
	v_fmac_f32_e32 v162, v160, v157
	v_fmac_f32_e32 v26, v64, v161
	v_fmac_f32_e32 v34, v64, v162
	v_fmac_f32_e32 v27, v65, v161
	v_fmac_f32_e32 v35, v65, v162
	v_fmac_f32_e32 v28, v66, v161
	v_fmac_f32_e32 v36, v66, v162
	v_fmac_f32_e32 v29, v67, v161
	v_fmac_f32_e32 v37, v67, v162
	v_fmac_f32_e32 v30, v68, v161
	v_fmac_f32_e32 v38, v68, v162
	v_fmac_f32_e32 v31, v69, v161
	v_fmac_f32_e32 v39, v69, v162
	v_fmac_f32_e32 v32, v70, v161
	v_fmac_f32_e32 v40, v70, v162
	v_fmac_f32_e32 v33, v71, v161
	v_fmac_f32_e32 v41, v71, v162
	ds_read_b128 v[64:67], v0 offset:32544
	ds_read_b128 v[68:71], v0 offset:32560
	ds_read_b64 v[98:99], v63 offset:33632
	ds_read_b64 v[96:97], v62 offset:33568
	ds_read_b128 v[88:91], v0 offset:33056
	ds_read_b128 v[92:95], v0 offset:33072
	s_waitcnt lgkmcnt(6)
	v_mul_f32_e64 v160, -v103, v102
	v_mul_f32_e32 v161, v102, v100
	v_mul_f32_e32 v162, v102, v101
	v_mul_f32_e32 v156, v26, v80
	v_mul_f32_e32 v157, v34, v80
	v_mul_f32_e32 v178, v26, v148
	v_mul_f32_e32 v194, v34, v148
	v_fmac_f32_e32 v156, v27, v81
	v_fmac_f32_e32 v157, v35, v81
	v_fmac_f32_e32 v178, v27, v149
	v_fmac_f32_e32 v194, v35, v149
	v_fmac_f32_e32 v156, v28, v82
	v_fmac_f32_e32 v157, v36, v82
	v_fmac_f32_e32 v178, v28, v150
	v_fmac_f32_e32 v194, v36, v150
	v_fmac_f32_e32 v156, v29, v83
	v_fmac_f32_e32 v157, v37, v83
	v_fmac_f32_e32 v178, v29, v151
	v_fmac_f32_e32 v194, v37, v151
	v_fmac_f32_e32 v156, v30, v84
	v_fmac_f32_e32 v157, v38, v84
	v_fmac_f32_e32 v178, v30, v152
	v_fmac_f32_e32 v194, v38, v152
	v_fmac_f32_e32 v156, v31, v85
	v_fmac_f32_e32 v157, v39, v85
	v_fmac_f32_e32 v178, v31, v153
	v_fmac_f32_e32 v194, v39, v153
	v_fmac_f32_e32 v156, v32, v86
	v_fmac_f32_e32 v157, v40, v86
	v_fmac_f32_e32 v178, v32, v154
	v_fmac_f32_e32 v194, v40, v154
	v_fmac_f32_e32 v156, v33, v87
	v_fmac_f32_e32 v157, v41, v87
	v_fmac_f32_e32 v178, v33, v155
	v_fmac_f32_e32 v194, v41, v155
	v_mul_f32_e32 v26, v103, v26
	v_mul_f32_e32 v34, v103, v34
	v_add_f32_dpp v156, v156, v156 quad_perm:[1,0,3,2] row_mask:0xf bank_mask:0xf bound_ctrl:1
	v_add_f32_dpp v157, v157, v157 quad_perm:[1,0,3,2] row_mask:0xf bank_mask:0xf bound_ctrl:1
	v_mul_f32_e32 v27, v103, v27
	v_mul_f32_e32 v35, v103, v35
	v_mul_f32_e32 v28, v103, v28
	v_mul_f32_e32 v36, v103, v36
	v_add_f32_dpp v156, v156, v156 quad_perm:[2,3,0,1] row_mask:0xf bank_mask:0xf bound_ctrl:1
	v_add_f32_dpp v157, v157, v157 quad_perm:[2,3,0,1] row_mask:0xf bank_mask:0xf bound_ctrl:1
	v_mul_f32_e32 v29, v103, v29
	v_mul_f32_e32 v37, v103, v37
	v_mul_f32_e32 v30, v103, v30
	v_mul_f32_e32 v38, v103, v38
	v_add_f32_dpp v156, v156, v156 row_half_mirror row_mask:0xf bank_mask:0xf bound_ctrl:1
	v_add_f32_dpp v157, v157, v157 row_half_mirror row_mask:0xf bank_mask:0xf bound_ctrl:1
	v_mul_f32_e32 v31, v103, v31
	v_mul_f32_e32 v39, v103, v39
	v_mul_f32_e32 v32, v103, v32
	v_mul_f32_e32 v40, v103, v40
	v_add_f32_dpp v156, v156, v156 row_ror:8 row_mask:0xf bank_mask:0xf bound_ctrl:1
	v_add_f32_dpp v157, v157, v157 row_ror:8 row_mask:0xf bank_mask:0xf bound_ctrl:1
	v_mul_f32_e32 v33, v103, v33
	v_mul_f32_e32 v41, v103, v41
	v_fmac_f32_e32 v161, v160, v156
	v_fmac_f32_e32 v162, v160, v157
	v_fmac_f32_e32 v26, v80, v161
	v_fmac_f32_e32 v34, v80, v162
	v_fmac_f32_e32 v27, v81, v161
	v_fmac_f32_e32 v35, v81, v162
	v_fmac_f32_e32 v28, v82, v161
	v_fmac_f32_e32 v36, v82, v162
	v_fmac_f32_e32 v29, v83, v161
	v_fmac_f32_e32 v37, v83, v162
	v_fmac_f32_e32 v30, v84, v161
	v_fmac_f32_e32 v38, v84, v162
	v_fmac_f32_e32 v31, v85, v161
	v_fmac_f32_e32 v39, v85, v162
	v_fmac_f32_e32 v32, v86, v161
	v_fmac_f32_e32 v40, v86, v162
	v_fmac_f32_e32 v33, v87, v161
	v_fmac_f32_e32 v41, v87, v162
	ds_read_b128 v[80:83], v0 offset:33648
	ds_read_b128 v[84:87], v0 offset:33664
	ds_read_b64 v[102:103], v63 offset:34736
	ds_read_b64 v[100:101], v62 offset:34672
	ds_read_b128 v[148:151], v0 offset:34160
	ds_read_b128 v[152:155], v0 offset:34176
	s_waitcnt lgkmcnt(6)
	v_mul_f32_e64 v160, -v99, v98
	v_mul_f32_e32 v161, v98, v96
	v_mul_f32_e32 v162, v98, v97
	v_mul_f32_e32 v156, v26, v64
	v_mul_f32_e32 v157, v34, v64
	v_mul_f32_e32 v179, v26, v72
	v_mul_f32_e32 v195, v34, v72
	v_fmac_f32_e32 v156, v27, v65
	v_fmac_f32_e32 v157, v35, v65
	v_fmac_f32_e32 v179, v27, v73
	v_fmac_f32_e32 v195, v35, v73
	v_fmac_f32_e32 v156, v28, v66
	v_fmac_f32_e32 v157, v36, v66
	v_fmac_f32_e32 v179, v28, v74
	v_fmac_f32_e32 v195, v36, v74
	v_fmac_f32_e32 v156, v29, v67
	v_fmac_f32_e32 v157, v37, v67
	v_fmac_f32_e32 v179, v29, v75
	v_fmac_f32_e32 v195, v37, v75
	v_fmac_f32_e32 v156, v30, v68
	v_fmac_f32_e32 v157, v38, v68
	v_fmac_f32_e32 v179, v30, v76
	v_fmac_f32_e32 v195, v38, v76
	v_fmac_f32_e32 v156, v31, v69
	v_fmac_f32_e32 v157, v39, v69
	v_fmac_f32_e32 v179, v31, v77
	v_fmac_f32_e32 v195, v39, v77
	v_fmac_f32_e32 v156, v32, v70
	v_fmac_f32_e32 v157, v40, v70
	v_fmac_f32_e32 v179, v32, v78
	v_fmac_f32_e32 v195, v40, v78
	v_fmac_f32_e32 v156, v33, v71
	v_fmac_f32_e32 v157, v41, v71
	v_fmac_f32_e32 v179, v33, v79
	v_fmac_f32_e32 v195, v41, v79
	v_mul_f32_e32 v26, v99, v26
	v_mul_f32_e32 v34, v99, v34
	v_add_f32_dpp v156, v156, v156 quad_perm:[1,0,3,2] row_mask:0xf bank_mask:0xf bound_ctrl:1
	v_add_f32_dpp v157, v157, v157 quad_perm:[1,0,3,2] row_mask:0xf bank_mask:0xf bound_ctrl:1
	v_mul_f32_e32 v27, v99, v27
	v_mul_f32_e32 v35, v99, v35
	v_mul_f32_e32 v28, v99, v28
	v_mul_f32_e32 v36, v99, v36
	v_add_f32_dpp v156, v156, v156 quad_perm:[2,3,0,1] row_mask:0xf bank_mask:0xf bound_ctrl:1
	v_add_f32_dpp v157, v157, v157 quad_perm:[2,3,0,1] row_mask:0xf bank_mask:0xf bound_ctrl:1
	v_mul_f32_e32 v29, v99, v29
	v_mul_f32_e32 v37, v99, v37
	v_mul_f32_e32 v30, v99, v30
	v_mul_f32_e32 v38, v99, v38
	v_add_f32_dpp v156, v156, v156 row_half_mirror row_mask:0xf bank_mask:0xf bound_ctrl:1
	v_add_f32_dpp v157, v157, v157 row_half_mirror row_mask:0xf bank_mask:0xf bound_ctrl:1
	v_mul_f32_e32 v31, v99, v31
	v_mul_f32_e32 v39, v99, v39
	v_mul_f32_e32 v32, v99, v32
	v_mul_f32_e32 v40, v99, v40
	v_add_f32_dpp v156, v156, v156 row_ror:8 row_mask:0xf bank_mask:0xf bound_ctrl:1
	v_add_f32_dpp v157, v157, v157 row_ror:8 row_mask:0xf bank_mask:0xf bound_ctrl:1
	v_mul_f32_e32 v33, v99, v33
	v_mul_f32_e32 v41, v99, v41
	v_fmac_f32_e32 v161, v160, v156
	v_fmac_f32_e32 v162, v160, v157
	v_fmac_f32_e32 v26, v64, v161
	v_fmac_f32_e32 v34, v64, v162
	v_fmac_f32_e32 v27, v65, v161
	v_fmac_f32_e32 v35, v65, v162
	v_fmac_f32_e32 v28, v66, v161
	v_fmac_f32_e32 v36, v66, v162
	v_fmac_f32_e32 v29, v67, v161
	v_fmac_f32_e32 v37, v67, v162
	v_fmac_f32_e32 v30, v68, v161
	v_fmac_f32_e32 v38, v68, v162
	v_fmac_f32_e32 v31, v69, v161
	v_fmac_f32_e32 v39, v69, v162
	v_fmac_f32_e32 v32, v70, v161
	v_fmac_f32_e32 v40, v70, v162
	v_fmac_f32_e32 v33, v71, v161
	v_fmac_f32_e32 v41, v71, v162
	ds_read_b128 v[64:67], v0 offset:34752
	ds_read_b128 v[68:71], v0 offset:34768
	ds_read_b64 v[98:99], v63 offset:35840
	ds_read_b64 v[96:97], v62 offset:35776
	ds_read_b128 v[72:75], v0 offset:35264
	ds_read_b128 v[76:79], v0 offset:35280
	s_waitcnt lgkmcnt(6)
	v_mul_f32_e64 v160, -v103, v102
	v_mul_f32_e32 v161, v102, v100
	v_mul_f32_e32 v162, v102, v101
	v_mul_f32_e32 v156, v26, v80
	v_mul_f32_e32 v157, v34, v80
	v_mul_f32_e32 v180, v26, v88
	v_mul_f32_e32 v196, v34, v88
	v_fmac_f32_e32 v156, v27, v81
	v_fmac_f32_e32 v157, v35, v81
	v_fmac_f32_e32 v180, v27, v89
	v_fmac_f32_e32 v196, v35, v89
	v_fmac_f32_e32 v156, v28, v82
	v_fmac_f32_e32 v157, v36, v82
	v_fmac_f32_e32 v180, v28, v90
	v_fmac_f32_e32 v196, v36, v90
	v_fmac_f32_e32 v156, v29, v83
	v_fmac_f32_e32 v157, v37, v83
	v_fmac_f32_e32 v180, v29, v91
	v_fmac_f32_e32 v196, v37, v91
	v_fmac_f32_e32 v156, v30, v84
	v_fmac_f32_e32 v157, v38, v84
	v_fmac_f32_e32 v180, v30, v92
	v_fmac_f32_e32 v196, v38, v92
	v_fmac_f32_e32 v156, v31, v85
	v_fmac_f32_e32 v157, v39, v85
	v_fmac_f32_e32 v180, v31, v93
	v_fmac_f32_e32 v196, v39, v93
	v_fmac_f32_e32 v156, v32, v86
	v_fmac_f32_e32 v157, v40, v86
	v_fmac_f32_e32 v180, v32, v94
	v_fmac_f32_e32 v196, v40, v94
	v_fmac_f32_e32 v156, v33, v87
	v_fmac_f32_e32 v157, v41, v87
	v_fmac_f32_e32 v180, v33, v95
	v_fmac_f32_e32 v196, v41, v95
	v_mul_f32_e32 v26, v103, v26
	v_mul_f32_e32 v34, v103, v34
	v_add_f32_dpp v156, v156, v156 quad_perm:[1,0,3,2] row_mask:0xf bank_mask:0xf bound_ctrl:1
	v_add_f32_dpp v157, v157, v157 quad_perm:[1,0,3,2] row_mask:0xf bank_mask:0xf bound_ctrl:1
	v_mul_f32_e32 v27, v103, v27
	v_mul_f32_e32 v35, v103, v35
	v_mul_f32_e32 v28, v103, v28
	v_mul_f32_e32 v36, v103, v36
	v_add_f32_dpp v156, v156, v156 quad_perm:[2,3,0,1] row_mask:0xf bank_mask:0xf bound_ctrl:1
	v_add_f32_dpp v157, v157, v157 quad_perm:[2,3,0,1] row_mask:0xf bank_mask:0xf bound_ctrl:1
	v_mul_f32_e32 v29, v103, v29
	v_mul_f32_e32 v37, v103, v37
	v_mul_f32_e32 v30, v103, v30
	v_mul_f32_e32 v38, v103, v38
	v_add_f32_dpp v156, v156, v156 row_half_mirror row_mask:0xf bank_mask:0xf bound_ctrl:1
	v_add_f32_dpp v157, v157, v157 row_half_mirror row_mask:0xf bank_mask:0xf bound_ctrl:1
	v_mul_f32_e32 v31, v103, v31
	v_mul_f32_e32 v39, v103, v39
	v_mul_f32_e32 v32, v103, v32
	v_mul_f32_e32 v40, v103, v40
	v_add_f32_dpp v156, v156, v156 row_ror:8 row_mask:0xf bank_mask:0xf bound_ctrl:1
	v_add_f32_dpp v157, v157, v157 row_ror:8 row_mask:0xf bank_mask:0xf bound_ctrl:1
	v_mul_f32_e32 v33, v103, v33
	v_mul_f32_e32 v41, v103, v41
	v_fmac_f32_e32 v161, v160, v156
	v_fmac_f32_e32 v162, v160, v157
	v_fmac_f32_e32 v26, v80, v161
	v_fmac_f32_e32 v34, v80, v162
	v_fmac_f32_e32 v27, v81, v161
	v_fmac_f32_e32 v35, v81, v162
	v_fmac_f32_e32 v28, v82, v161
	v_fmac_f32_e32 v36, v82, v162
	v_fmac_f32_e32 v29, v83, v161
	v_fmac_f32_e32 v37, v83, v162
	v_fmac_f32_e32 v30, v84, v161
	v_fmac_f32_e32 v38, v84, v162
	v_fmac_f32_e32 v31, v85, v161
	v_fmac_f32_e32 v39, v85, v162
	v_fmac_f32_e32 v32, v86, v161
	v_fmac_f32_e32 v40, v86, v162
	v_fmac_f32_e32 v33, v87, v161
	v_fmac_f32_e32 v41, v87, v162
	ds_read_b128 v[80:83], v0 offset:35856
	ds_read_b128 v[84:87], v0 offset:35872
	ds_read_b64 v[102:103], v63 offset:36944
	ds_read_b64 v[100:101], v62 offset:36880
	ds_read_b128 v[88:91], v0 offset:36368
	ds_read_b128 v[92:95], v0 offset:36384
	s_waitcnt lgkmcnt(6)
	v_mul_f32_e64 v160, -v99, v98
	v_mul_f32_e32 v161, v98, v96
	v_mul_f32_e32 v162, v98, v97
	v_mul_f32_e32 v156, v26, v64
	v_mul_f32_e32 v157, v34, v64
	v_mul_f32_e32 v181, v26, v148
	v_mul_f32_e32 v197, v34, v148
	v_fmac_f32_e32 v156, v27, v65
	v_fmac_f32_e32 v157, v35, v65
	v_fmac_f32_e32 v181, v27, v149
	v_fmac_f32_e32 v197, v35, v149
	v_fmac_f32_e32 v156, v28, v66
	v_fmac_f32_e32 v157, v36, v66
	v_fmac_f32_e32 v181, v28, v150
	v_fmac_f32_e32 v197, v36, v150
	v_fmac_f32_e32 v156, v29, v67
	v_fmac_f32_e32 v157, v37, v67
	v_fmac_f32_e32 v181, v29, v151
	v_fmac_f32_e32 v197, v37, v151
	v_fmac_f32_e32 v156, v30, v68
	v_fmac_f32_e32 v157, v38, v68
	v_fmac_f32_e32 v181, v30, v152
	v_fmac_f32_e32 v197, v38, v152
	v_fmac_f32_e32 v156, v31, v69
	v_fmac_f32_e32 v157, v39, v69
	v_fmac_f32_e32 v181, v31, v153
	v_fmac_f32_e32 v197, v39, v153
	v_fmac_f32_e32 v156, v32, v70
	v_fmac_f32_e32 v157, v40, v70
	v_fmac_f32_e32 v181, v32, v154
	v_fmac_f32_e32 v197, v40, v154
	v_fmac_f32_e32 v156, v33, v71
	v_fmac_f32_e32 v157, v41, v71
	v_fmac_f32_e32 v181, v33, v155
	v_fmac_f32_e32 v197, v41, v155
	v_mul_f32_e32 v26, v99, v26
	v_mul_f32_e32 v34, v99, v34
	v_add_f32_dpp v156, v156, v156 quad_perm:[1,0,3,2] row_mask:0xf bank_mask:0xf bound_ctrl:1
	v_add_f32_dpp v157, v157, v157 quad_perm:[1,0,3,2] row_mask:0xf bank_mask:0xf bound_ctrl:1
	v_mul_f32_e32 v27, v99, v27
	v_mul_f32_e32 v35, v99, v35
	v_mul_f32_e32 v28, v99, v28
	v_mul_f32_e32 v36, v99, v36
	v_add_f32_dpp v156, v156, v156 quad_perm:[2,3,0,1] row_mask:0xf bank_mask:0xf bound_ctrl:1
	v_add_f32_dpp v157, v157, v157 quad_perm:[2,3,0,1] row_mask:0xf bank_mask:0xf bound_ctrl:1
	v_mul_f32_e32 v29, v99, v29
	v_mul_f32_e32 v37, v99, v37
	v_mul_f32_e32 v30, v99, v30
	v_mul_f32_e32 v38, v99, v38
	v_add_f32_dpp v156, v156, v156 row_half_mirror row_mask:0xf bank_mask:0xf bound_ctrl:1
	v_add_f32_dpp v157, v157, v157 row_half_mirror row_mask:0xf bank_mask:0xf bound_ctrl:1
	v_mul_f32_e32 v31, v99, v31
	v_mul_f32_e32 v39, v99, v39
	v_mul_f32_e32 v32, v99, v32
	v_mul_f32_e32 v40, v99, v40
	v_add_f32_dpp v156, v156, v156 row_ror:8 row_mask:0xf bank_mask:0xf bound_ctrl:1
	v_add_f32_dpp v157, v157, v157 row_ror:8 row_mask:0xf bank_mask:0xf bound_ctrl:1
	v_mul_f32_e32 v33, v99, v33
	v_mul_f32_e32 v41, v99, v41
	v_fmac_f32_e32 v161, v160, v156
	v_fmac_f32_e32 v162, v160, v157
	v_fmac_f32_e32 v26, v64, v161
	v_fmac_f32_e32 v34, v64, v162
	v_fmac_f32_e32 v27, v65, v161
	v_fmac_f32_e32 v35, v65, v162
	v_fmac_f32_e32 v28, v66, v161
	v_fmac_f32_e32 v36, v66, v162
	v_fmac_f32_e32 v29, v67, v161
	v_fmac_f32_e32 v37, v67, v162
	v_fmac_f32_e32 v30, v68, v161
	v_fmac_f32_e32 v38, v68, v162
	v_fmac_f32_e32 v31, v69, v161
	v_fmac_f32_e32 v39, v69, v162
	v_fmac_f32_e32 v32, v70, v161
	v_fmac_f32_e32 v40, v70, v162
	v_fmac_f32_e32 v33, v71, v161
	v_fmac_f32_e32 v41, v71, v162
	ds_read_b128 v[64:67], v0 offset:36960
	ds_read_b128 v[68:71], v0 offset:36976
	ds_read_b64 v[98:99], v63 offset:38048
	ds_read_b64 v[96:97], v62 offset:37984
	ds_read_b128 v[148:151], v0 offset:37472
	ds_read_b128 v[152:155], v0 offset:37488
	s_waitcnt lgkmcnt(6)
	v_mul_f32_e64 v160, -v103, v102
	v_mul_f32_e32 v161, v102, v100
	v_mul_f32_e32 v162, v102, v101
	v_mul_f32_e32 v156, v26, v80
	v_mul_f32_e32 v157, v34, v80
	v_mul_f32_e32 v182, v26, v72
	v_mul_f32_e32 v198, v34, v72
	v_fmac_f32_e32 v156, v27, v81
	v_fmac_f32_e32 v157, v35, v81
	v_fmac_f32_e32 v182, v27, v73
	v_fmac_f32_e32 v198, v35, v73
	v_fmac_f32_e32 v156, v28, v82
	v_fmac_f32_e32 v157, v36, v82
	v_fmac_f32_e32 v182, v28, v74
	v_fmac_f32_e32 v198, v36, v74
	v_fmac_f32_e32 v156, v29, v83
	v_fmac_f32_e32 v157, v37, v83
	v_fmac_f32_e32 v182, v29, v75
	v_fmac_f32_e32 v198, v37, v75
	v_fmac_f32_e32 v156, v30, v84
	v_fmac_f32_e32 v157, v38, v84
	v_fmac_f32_e32 v182, v30, v76
	v_fmac_f32_e32 v198, v38, v76
	v_fmac_f32_e32 v156, v31, v85
	v_fmac_f32_e32 v157, v39, v85
	v_fmac_f32_e32 v182, v31, v77
	v_fmac_f32_e32 v198, v39, v77
	v_fmac_f32_e32 v156, v32, v86
	v_fmac_f32_e32 v157, v40, v86
	v_fmac_f32_e32 v182, v32, v78
	v_fmac_f32_e32 v198, v40, v78
	v_fmac_f32_e32 v156, v33, v87
	v_fmac_f32_e32 v157, v41, v87
	v_fmac_f32_e32 v182, v33, v79
	v_fmac_f32_e32 v198, v41, v79
	v_mul_f32_e32 v26, v103, v26
	v_mul_f32_e32 v34, v103, v34
	v_add_f32_dpp v156, v156, v156 quad_perm:[1,0,3,2] row_mask:0xf bank_mask:0xf bound_ctrl:1
	v_add_f32_dpp v157, v157, v157 quad_perm:[1,0,3,2] row_mask:0xf bank_mask:0xf bound_ctrl:1
	v_mul_f32_e32 v27, v103, v27
	v_mul_f32_e32 v35, v103, v35
	v_mul_f32_e32 v28, v103, v28
	v_mul_f32_e32 v36, v103, v36
	v_add_f32_dpp v156, v156, v156 quad_perm:[2,3,0,1] row_mask:0xf bank_mask:0xf bound_ctrl:1
	v_add_f32_dpp v157, v157, v157 quad_perm:[2,3,0,1] row_mask:0xf bank_mask:0xf bound_ctrl:1
	v_mul_f32_e32 v29, v103, v29
	v_mul_f32_e32 v37, v103, v37
	v_mul_f32_e32 v30, v103, v30
	v_mul_f32_e32 v38, v103, v38
	v_add_f32_dpp v156, v156, v156 row_half_mirror row_mask:0xf bank_mask:0xf bound_ctrl:1
	v_add_f32_dpp v157, v157, v157 row_half_mirror row_mask:0xf bank_mask:0xf bound_ctrl:1
	v_mul_f32_e32 v31, v103, v31
	v_mul_f32_e32 v39, v103, v39
	v_mul_f32_e32 v32, v103, v32
	v_mul_f32_e32 v40, v103, v40
	v_add_f32_dpp v156, v156, v156 row_ror:8 row_mask:0xf bank_mask:0xf bound_ctrl:1
	v_add_f32_dpp v157, v157, v157 row_ror:8 row_mask:0xf bank_mask:0xf bound_ctrl:1
	v_mul_f32_e32 v33, v103, v33
	v_mul_f32_e32 v41, v103, v41
	v_fmac_f32_e32 v161, v160, v156
	v_fmac_f32_e32 v162, v160, v157
	v_fmac_f32_e32 v26, v80, v161
	v_fmac_f32_e32 v34, v80, v162
	v_fmac_f32_e32 v27, v81, v161
	v_fmac_f32_e32 v35, v81, v162
	v_fmac_f32_e32 v28, v82, v161
	v_fmac_f32_e32 v36, v82, v162
	v_fmac_f32_e32 v29, v83, v161
	v_fmac_f32_e32 v37, v83, v162
	v_fmac_f32_e32 v30, v84, v161
	v_fmac_f32_e32 v38, v84, v162
	v_fmac_f32_e32 v31, v85, v161
	v_fmac_f32_e32 v39, v85, v162
	v_fmac_f32_e32 v32, v86, v161
	v_fmac_f32_e32 v40, v86, v162
	v_fmac_f32_e32 v33, v87, v161
	v_fmac_f32_e32 v41, v87, v162
	ds_read_b128 v[80:83], v0 offset:38064
	ds_read_b128 v[84:87], v0 offset:38080
	ds_read_b64 v[102:103], v63 offset:39152
	ds_read_b64 v[100:101], v62 offset:39088
	ds_read_b128 v[72:75], v0 offset:38576
	ds_read_b128 v[76:79], v0 offset:38592
	s_waitcnt lgkmcnt(6)
	v_mul_f32_e64 v160, -v99, v98
	v_mul_f32_e32 v161, v98, v96
	v_mul_f32_e32 v162, v98, v97
	v_mul_f32_e32 v156, v26, v64
	v_mul_f32_e32 v157, v34, v64
	v_mul_f32_e32 v183, v26, v88
	v_mul_f32_e32 v199, v34, v88
	v_fmac_f32_e32 v156, v27, v65
	v_fmac_f32_e32 v157, v35, v65
	v_fmac_f32_e32 v183, v27, v89
	v_fmac_f32_e32 v199, v35, v89
	v_fmac_f32_e32 v156, v28, v66
	v_fmac_f32_e32 v157, v36, v66
	v_fmac_f32_e32 v183, v28, v90
	v_fmac_f32_e32 v199, v36, v90
	v_fmac_f32_e32 v156, v29, v67
	v_fmac_f32_e32 v157, v37, v67
	v_fmac_f32_e32 v183, v29, v91
	v_fmac_f32_e32 v199, v37, v91
	v_fmac_f32_e32 v156, v30, v68
	v_fmac_f32_e32 v157, v38, v68
	v_fmac_f32_e32 v183, v30, v92
	v_fmac_f32_e32 v199, v38, v92
	v_fmac_f32_e32 v156, v31, v69
	v_fmac_f32_e32 v157, v39, v69
	v_fmac_f32_e32 v183, v31, v93
	v_fmac_f32_e32 v199, v39, v93
	v_fmac_f32_e32 v156, v32, v70
	v_fmac_f32_e32 v157, v40, v70
	v_fmac_f32_e32 v183, v32, v94
	v_fmac_f32_e32 v199, v40, v94
	v_fmac_f32_e32 v156, v33, v71
	v_fmac_f32_e32 v157, v41, v71
	v_fmac_f32_e32 v183, v33, v95
	v_fmac_f32_e32 v199, v41, v95
	v_mul_f32_e32 v26, v99, v26
	v_mul_f32_e32 v34, v99, v34
	v_add_f32_dpp v156, v156, v156 quad_perm:[1,0,3,2] row_mask:0xf bank_mask:0xf bound_ctrl:1
	v_add_f32_dpp v157, v157, v157 quad_perm:[1,0,3,2] row_mask:0xf bank_mask:0xf bound_ctrl:1
	v_mul_f32_e32 v27, v99, v27
	v_mul_f32_e32 v35, v99, v35
	v_mul_f32_e32 v28, v99, v28
	v_mul_f32_e32 v36, v99, v36
	v_add_f32_dpp v156, v156, v156 quad_perm:[2,3,0,1] row_mask:0xf bank_mask:0xf bound_ctrl:1
	v_add_f32_dpp v157, v157, v157 quad_perm:[2,3,0,1] row_mask:0xf bank_mask:0xf bound_ctrl:1
	v_mul_f32_e32 v29, v99, v29
	v_mul_f32_e32 v37, v99, v37
	v_mul_f32_e32 v30, v99, v30
	v_mul_f32_e32 v38, v99, v38
	v_add_f32_dpp v156, v156, v156 row_half_mirror row_mask:0xf bank_mask:0xf bound_ctrl:1
	v_add_f32_dpp v157, v157, v157 row_half_mirror row_mask:0xf bank_mask:0xf bound_ctrl:1
	v_mul_f32_e32 v31, v99, v31
	v_mul_f32_e32 v39, v99, v39
	v_mul_f32_e32 v32, v99, v32
	v_mul_f32_e32 v40, v99, v40
	v_add_f32_dpp v156, v156, v156 row_ror:8 row_mask:0xf bank_mask:0xf bound_ctrl:1
	v_add_f32_dpp v157, v157, v157 row_ror:8 row_mask:0xf bank_mask:0xf bound_ctrl:1
	v_mul_f32_e32 v33, v99, v33
	v_mul_f32_e32 v41, v99, v41
	v_fmac_f32_e32 v161, v160, v156
	v_fmac_f32_e32 v162, v160, v157
	v_fmac_f32_e32 v26, v64, v161
	v_fmac_f32_e32 v34, v64, v162
	v_fmac_f32_e32 v27, v65, v161
	v_fmac_f32_e32 v35, v65, v162
	v_fmac_f32_e32 v28, v66, v161
	v_fmac_f32_e32 v36, v66, v162
	v_fmac_f32_e32 v29, v67, v161
	v_fmac_f32_e32 v37, v67, v162
	v_fmac_f32_e32 v30, v68, v161
	v_fmac_f32_e32 v38, v68, v162
	v_fmac_f32_e32 v31, v69, v161
	v_fmac_f32_e32 v39, v69, v162
	v_fmac_f32_e32 v32, v70, v161
	v_fmac_f32_e32 v40, v70, v162
	v_fmac_f32_e32 v33, v71, v161
	v_fmac_f32_e32 v41, v71, v162
	s_waitcnt lgkmcnt(0)
	v_mul_f32_e64 v160, -v103, v102
	v_mul_f32_e32 v161, v102, v100
	v_mul_f32_e32 v162, v102, v101
	v_mul_f32_e32 v156, v26, v80
	v_mul_f32_e32 v157, v34, v80
	v_mul_f32_e32 v184, v26, v148
	v_mul_f32_e32 v200, v34, v148
	v_fmac_f32_e32 v156, v27, v81
	v_fmac_f32_e32 v157, v35, v81
	v_fmac_f32_e32 v184, v27, v149
	v_fmac_f32_e32 v200, v35, v149
	v_fmac_f32_e32 v156, v28, v82
	v_fmac_f32_e32 v157, v36, v82
	v_fmac_f32_e32 v184, v28, v150
	v_fmac_f32_e32 v200, v36, v150
	v_fmac_f32_e32 v156, v29, v83
	v_fmac_f32_e32 v157, v37, v83
	v_fmac_f32_e32 v184, v29, v151
	v_fmac_f32_e32 v200, v37, v151
	v_fmac_f32_e32 v156, v30, v84
	v_fmac_f32_e32 v157, v38, v84
	v_fmac_f32_e32 v184, v30, v152
	v_fmac_f32_e32 v200, v38, v152
	v_fmac_f32_e32 v156, v31, v85
	v_fmac_f32_e32 v157, v39, v85
	v_fmac_f32_e32 v184, v31, v153
	v_fmac_f32_e32 v200, v39, v153
	v_fmac_f32_e32 v156, v32, v86
	v_fmac_f32_e32 v157, v40, v86
	v_fmac_f32_e32 v184, v32, v154
	v_fmac_f32_e32 v200, v40, v154
	v_fmac_f32_e32 v156, v33, v87
	v_fmac_f32_e32 v157, v41, v87
	v_fmac_f32_e32 v184, v33, v155
	v_fmac_f32_e32 v200, v41, v155
	v_mul_f32_e32 v26, v103, v26
	v_mul_f32_e32 v34, v103, v34
	v_add_f32_dpp v156, v156, v156 quad_perm:[1,0,3,2] row_mask:0xf bank_mask:0xf bound_ctrl:1
	v_add_f32_dpp v157, v157, v157 quad_perm:[1,0,3,2] row_mask:0xf bank_mask:0xf bound_ctrl:1
	v_mul_f32_e32 v27, v103, v27
	v_mul_f32_e32 v35, v103, v35
	v_mul_f32_e32 v28, v103, v28
	v_mul_f32_e32 v36, v103, v36
	v_add_f32_dpp v156, v156, v156 quad_perm:[2,3,0,1] row_mask:0xf bank_mask:0xf bound_ctrl:1
	v_add_f32_dpp v157, v157, v157 quad_perm:[2,3,0,1] row_mask:0xf bank_mask:0xf bound_ctrl:1
	v_mul_f32_e32 v29, v103, v29
	v_mul_f32_e32 v37, v103, v37
	v_mul_f32_e32 v30, v103, v30
	v_mul_f32_e32 v38, v103, v38
	v_add_f32_dpp v156, v156, v156 row_half_mirror row_mask:0xf bank_mask:0xf bound_ctrl:1
	v_add_f32_dpp v157, v157, v157 row_half_mirror row_mask:0xf bank_mask:0xf bound_ctrl:1
	v_mul_f32_e32 v31, v103, v31
	v_mul_f32_e32 v39, v103, v39
	v_mul_f32_e32 v32, v103, v32
	v_mul_f32_e32 v40, v103, v40
	v_add_f32_dpp v156, v156, v156 row_ror:8 row_mask:0xf bank_mask:0xf bound_ctrl:1
	v_add_f32_dpp v157, v157, v157 row_ror:8 row_mask:0xf bank_mask:0xf bound_ctrl:1
	v_mul_f32_e32 v33, v103, v33
	v_mul_f32_e32 v41, v103, v41
	v_fmac_f32_e32 v161, v160, v156
	v_fmac_f32_e32 v162, v160, v157
	v_fmac_f32_e32 v26, v80, v161
	v_fmac_f32_e32 v34, v80, v162
	v_fmac_f32_e32 v27, v81, v161
	v_fmac_f32_e32 v35, v81, v162
	v_fmac_f32_e32 v28, v82, v161
	v_fmac_f32_e32 v36, v82, v162
	v_fmac_f32_e32 v29, v83, v161
	v_fmac_f32_e32 v37, v83, v162
	v_fmac_f32_e32 v30, v84, v161
	v_fmac_f32_e32 v38, v84, v162
	v_fmac_f32_e32 v31, v85, v161
	v_fmac_f32_e32 v39, v85, v162
	v_fmac_f32_e32 v32, v86, v161
	v_fmac_f32_e32 v40, v86, v162
	v_fmac_f32_e32 v33, v87, v161
	v_fmac_f32_e32 v41, v87, v162
	v_mul_f32_e32 v185, v26, v72
	v_mul_f32_e32 v201, v34, v72
	v_mov_b32_e32 v42, v26
	v_mov_b32_e32 v43, v27
	v_fmac_f32_e32 v185, v27, v73
	v_fmac_f32_e32 v201, v35, v73
	v_mov_b32_e32 v44, v28
	v_mov_b32_e32 v45, v29
	v_fmac_f32_e32 v185, v28, v74
	v_fmac_f32_e32 v201, v36, v74
	v_mov_b32_e32 v50, v30
	v_mov_b32_e32 v51, v31
	v_fmac_f32_e32 v185, v29, v75
	v_fmac_f32_e32 v201, v37, v75
	v_mov_b32_e32 v52, v32
	v_mov_b32_e32 v53, v33
	v_fmac_f32_e32 v185, v30, v76
	v_fmac_f32_e32 v201, v38, v76
	v_mov_b32_e32 v46, v34
	v_mov_b32_e32 v47, v35
	v_fmac_f32_e32 v185, v31, v77
	v_fmac_f32_e32 v201, v39, v77
	v_mov_b32_e32 v48, v36
	v_mov_b32_e32 v49, v37
	v_fmac_f32_e32 v185, v32, v78
	v_fmac_f32_e32 v201, v40, v78
	v_mov_b32_e32 v54, v38
	v_mov_b32_e32 v55, v39
	v_fmac_f32_e32 v185, v33, v79
	v_fmac_f32_e32 v201, v41, v79
	v_mov_b32_e32 v56, v40
	v_mov_b32_e32 v57, v41
	s_nop 0
	v_add_f32_dpp v170, v170, v170 row_ror:8 row_mask:0xf bank_mask:0xf bound_ctrl:1
	v_add_f32_dpp v186, v186, v186 row_ror:8 row_mask:0xf bank_mask:0xf bound_ctrl:1
	v_add_f32_dpp v171, v171, v171 row_ror:8 row_mask:0xf bank_mask:0xf bound_ctrl:1
	v_add_f32_dpp v187, v187, v187 row_ror:8 row_mask:0xf bank_mask:0xf bound_ctrl:1
	v_add_f32_dpp v172, v172, v172 row_ror:8 row_mask:0xf bank_mask:0xf bound_ctrl:1
	v_add_f32_dpp v188, v188, v188 row_ror:8 row_mask:0xf bank_mask:0xf bound_ctrl:1
	v_add_f32_dpp v173, v173, v173 row_ror:8 row_mask:0xf bank_mask:0xf bound_ctrl:1
	v_add_f32_dpp v189, v189, v189 row_ror:8 row_mask:0xf bank_mask:0xf bound_ctrl:1
	v_add_f32_dpp v174, v174, v174 row_ror:8 row_mask:0xf bank_mask:0xf bound_ctrl:1
	v_add_f32_dpp v190, v190, v190 row_ror:8 row_mask:0xf bank_mask:0xf bound_ctrl:1
	v_add_f32_dpp v175, v175, v175 row_ror:8 row_mask:0xf bank_mask:0xf bound_ctrl:1
	v_add_f32_dpp v191, v191, v191 row_ror:8 row_mask:0xf bank_mask:0xf bound_ctrl:1
	v_add_f32_dpp v176, v176, v176 row_ror:8 row_mask:0xf bank_mask:0xf bound_ctrl:1
	v_add_f32_dpp v192, v192, v192 row_ror:8 row_mask:0xf bank_mask:0xf bound_ctrl:1
	v_add_f32_dpp v177, v177, v177 row_ror:8 row_mask:0xf bank_mask:0xf bound_ctrl:1
	v_add_f32_dpp v193, v193, v193 row_ror:8 row_mask:0xf bank_mask:0xf bound_ctrl:1
	v_add_f32_dpp v170, v178, v178 row_ror:8 row_mask:0xf bank_mask:0xc bound_ctrl:1
	v_add_f32_dpp v186, v194, v194 row_ror:8 row_mask:0xf bank_mask:0xc bound_ctrl:1
	v_add_f32_dpp v171, v179, v179 row_ror:8 row_mask:0xf bank_mask:0xc bound_ctrl:1
	v_add_f32_dpp v187, v195, v195 row_ror:8 row_mask:0xf bank_mask:0xc bound_ctrl:1
	v_add_f32_dpp v172, v180, v180 row_ror:8 row_mask:0xf bank_mask:0xc bound_ctrl:1
	v_add_f32_dpp v188, v196, v196 row_ror:8 row_mask:0xf bank_mask:0xc bound_ctrl:1
	v_add_f32_dpp v173, v181, v181 row_ror:8 row_mask:0xf bank_mask:0xc bound_ctrl:1
	v_add_f32_dpp v189, v197, v197 row_ror:8 row_mask:0xf bank_mask:0xc bound_ctrl:1
	v_add_f32_dpp v174, v182, v182 row_ror:8 row_mask:0xf bank_mask:0xc bound_ctrl:1
	v_add_f32_dpp v190, v198, v198 row_ror:8 row_mask:0xf bank_mask:0xc bound_ctrl:1
	v_add_f32_dpp v175, v183, v183 row_ror:8 row_mask:0xf bank_mask:0xc bound_ctrl:1
	v_add_f32_dpp v191, v199, v199 row_ror:8 row_mask:0xf bank_mask:0xc bound_ctrl:1
	v_add_f32_dpp v176, v184, v184 row_ror:8 row_mask:0xf bank_mask:0xc bound_ctrl:1
	v_add_f32_dpp v192, v200, v200 row_ror:8 row_mask:0xf bank_mask:0xc bound_ctrl:1
	v_add_f32_dpp v177, v185, v185 row_ror:8 row_mask:0xf bank_mask:0xc bound_ctrl:1
	v_add_f32_dpp v193, v201, v201 row_ror:8 row_mask:0xf bank_mask:0xc bound_ctrl:1
	v_add_f32_dpp v170, v170, v170 row_ror:12 row_mask:0xf bank_mask:0x5 bound_ctrl:1
	v_add_f32_dpp v186, v186, v186 row_ror:12 row_mask:0xf bank_mask:0x5 bound_ctrl:1
	v_add_f32_dpp v171, v171, v171 row_ror:12 row_mask:0xf bank_mask:0x5 bound_ctrl:1
	v_add_f32_dpp v187, v187, v187 row_ror:12 row_mask:0xf bank_mask:0x5 bound_ctrl:1
	v_add_f32_dpp v172, v172, v172 row_ror:12 row_mask:0xf bank_mask:0x5 bound_ctrl:1
	v_add_f32_dpp v188, v188, v188 row_ror:12 row_mask:0xf bank_mask:0x5 bound_ctrl:1
	v_add_f32_dpp v173, v173, v173 row_ror:12 row_mask:0xf bank_mask:0x5 bound_ctrl:1
	v_add_f32_dpp v189, v189, v189 row_ror:12 row_mask:0xf bank_mask:0x5 bound_ctrl:1
	v_and_b32_e32 v156, 2, v109
	v_add_f32_dpp v170, v174, v174 row_ror:4 row_mask:0xf bank_mask:0xa bound_ctrl:1
	v_add_f32_dpp v186, v190, v190 row_ror:4 row_mask:0xf bank_mask:0xa bound_ctrl:1
	v_add_f32_dpp v171, v175, v175 row_ror:4 row_mask:0xf bank_mask:0xa bound_ctrl:1
	v_add_f32_dpp v187, v191, v191 row_ror:4 row_mask:0xf bank_mask:0xa bound_ctrl:1
	v_add_f32_dpp v172, v176, v176 row_ror:4 row_mask:0xf bank_mask:0xa bound_ctrl:1
	v_add_f32_dpp v188, v192, v192 row_ror:4 row_mask:0xf bank_mask:0xa bound_ctrl:1
	v_add_f32_dpp v173, v177, v177 row_ror:4 row_mask:0xf bank_mask:0xa bound_ctrl:1
	v_add_f32_dpp v189, v193, v193 row_ror:4 row_mask:0xf bank_mask:0xa bound_ctrl:1
	v_cmp_ne_u32_e32 vcc, 0, v156
	v_ashrrev_i32_e32 v115, 31, v114
	s_nop 0
	v_cndmask_b32_e32 v157, v170, v172, vcc
	v_cndmask_b32_e32 v159, v172, v170, vcc
	v_cndmask_b32_e32 v162, v186, v188, vcc
	v_cndmask_b32_e32 v164, v188, v186, vcc
	v_cndmask_b32_e32 v158, v171, v173, vcc
	v_cndmask_b32_e32 v160, v173, v171, vcc
	v_cndmask_b32_e32 v163, v187, v189, vcc
	v_cndmask_b32_e32 v165, v189, v187, vcc
	v_and_b32_e32 v156, 1, v109
	v_add_f32_dpp v157, v159, v157 quad_perm:[2,3,0,1] row_mask:0xf bank_mask:0xf bound_ctrl:1
	v_add_f32_dpp v162, v164, v162 quad_perm:[2,3,0,1] row_mask:0xf bank_mask:0xf bound_ctrl:1
	v_add_f32_dpp v158, v160, v158 quad_perm:[2,3,0,1] row_mask:0xf bank_mask:0xf bound_ctrl:1
	v_add_f32_dpp v163, v165, v163 quad_perm:[2,3,0,1] row_mask:0xf bank_mask:0xf bound_ctrl:1
	v_cmp_ne_u32_e32 vcc, 0, v156
	s_nop 0
	s_nop 0
	v_cndmask_b32_e32 v159, v158, v157, vcc
	v_cndmask_b32_e32 v164, v163, v162, vcc
	v_cndmask_b32_e32 v160, v157, v158, vcc
	v_cndmask_b32_e32 v165, v162, v163, vcc
	s_nop 0
	v_add_f32_dpp v58, v159, v160 quad_perm:[1,0,3,2] row_mask:0xf bank_mask:0xf bound_ctrl:1
	v_add_f32_dpp v59, v164, v165 quad_perm:[1,0,3,2] row_mask:0xf bank_mask:0xf bound_ctrl:1
	v_lshlrev_b64 v[60:61], 12, v[114:115]
	v_lshl_add_u64 v[60:61], v[110:111], 0, v[60:61]
	s_mov_b64 s[2:3], 0

.LBB0_1239:
	v_add_u32_e32 v0, s1, v108
	v_lshl_add_u32 v62, v120, 2, s1
	ds_read_b128 v[68:71], v0 offset:256
	ds_read_b64 v[152:153], v62 offset:1280
	ds_read_b128 v[76:79], v0 offset:768
	ds_read_b128 v[64:67], v0 offset:0
	ds_read_b128 v[72:75], v0 offset:512
	ds_read_b128 v[96:99], v0 offset:1024
	ds_read_b128 v[84:87], v0 offset:1600
	ds_read_b64 v[154:155], v62 offset:2624
	ds_read_b128 v[92:95], v0 offset:2112
	ds_read_b128 v[80:83], v0 offset:1344
	ds_read_b128 v[88:91], v0 offset:1856
	ds_read_b128 v[100:103], v0 offset:2368
	s_waitcnt lgkmcnt(6)
	v_mul_f32_e32 v156, v26, v68
	v_mul_f32_e32 v157, v34, v68
	v_fmac_f32_e32 v156, v27, v69
	v_fmac_f32_e32 v157, v35, v69
	v_fmac_f32_e32 v156, v28, v70
	v_fmac_f32_e32 v157, v36, v70
	v_fmac_f32_e32 v156, v29, v71
	v_fmac_f32_e32 v157, v37, v71
	v_mul_f32_e32 v160, v76, v152
	v_mul_f32_e32 v161, v77, v152
	v_add_f32_dpp v156, v156, v156 quad_perm:[1,0,3,2] row_mask:0xf bank_mask:0xf bound_ctrl:1
	v_add_f32_dpp v157, v157, v157 quad_perm:[1,0,3,2] row_mask:0xf bank_mask:0xf bound_ctrl:1
	v_mul_f32_e32 v162, v78, v152
	v_mul_f32_e32 v163, v79, v152
	v_mul_f32_e32 v164, v76, v153
	v_mul_f32_e32 v165, v77, v153
	v_add_f32_dpp v156, v156, v156 quad_perm:[2,3,0,1] row_mask:0xf bank_mask:0xf bound_ctrl:1
	v_add_f32_dpp v157, v157, v157 quad_perm:[2,3,0,1] row_mask:0xf bank_mask:0xf bound_ctrl:1
	v_mul_f32_e32 v166, v78, v153
	v_mul_f32_e32 v167, v79, v153
	v_fmac_f32_e32 v160, v26, v64
	v_fmac_f32_e32 v161, v27, v65
	v_add_f32_dpp v156, v156, v156 row_half_mirror row_mask:0xf bank_mask:0xf bound_ctrl:1
	v_add_f32_dpp v157, v157, v157 row_half_mirror row_mask:0xf bank_mask:0xf bound_ctrl:1
	v_fmac_f32_e32 v162, v28, v66
	v_fmac_f32_e32 v163, v29, v67
	v_fmac_f32_e32 v164, v34, v64
	v_fmac_f32_e32 v165, v35, v65
	v_add_f32_dpp v156, v156, v156 row_ror:8 row_mask:0xf bank_mask:0xf bound_ctrl:1
	v_add_f32_dpp v157, v157, v157 row_ror:8 row_mask:0xf bank_mask:0xf bound_ctrl:1
	v_fmac_f32_e32 v166, v36, v66
	v_fmac_f32_e32 v167, v37, v67
	v_fmac_f32_e32 v160, v72, v156
	v_fmac_f32_e32 v164, v72, v157
	v_fmac_f32_e32 v161, v73, v156
	v_fmac_f32_e32 v165, v73, v157
	v_fmac_f32_e32 v162, v74, v156
	v_fmac_f32_e32 v166, v74, v157
	v_fmac_f32_e32 v163, v75, v156
	v_fmac_f32_e32 v167, v75, v157
	ds_read_b128 v[68:71], v0 offset:2944
	ds_read_b64 v[152:153], v62 offset:3968
	ds_read_b128 v[76:79], v0 offset:3456
	ds_read_b128 v[64:67], v0 offset:2688
	ds_read_b128 v[72:75], v0 offset:3200
	ds_read_b128 v[148:151], v0 offset:3712
	s_waitcnt lgkmcnt(6)
	v_mul_f32_e32 v156, v160, v84
	v_mul_f32_e32 v157, v164, v84
	v_mul_f32_e32 v170, v160, v96
	v_mul_f32_e32 v186, v164, v96
	v_fmac_f32_e32 v156, v161, v85
	v_fmac_f32_e32 v157, v165, v85
	v_fmac_f32_e32 v170, v161, v97
	v_fmac_f32_e32 v186, v165, v97
	v_fmac_f32_e32 v156, v162, v86
	v_fmac_f32_e32 v157, v166, v86
	v_fmac_f32_e32 v170, v162, v98
	v_fmac_f32_e32 v186, v166, v98
	v_fmac_f32_e32 v156, v163, v87
	v_fmac_f32_e32 v157, v167, v87
	v_fmac_f32_e32 v170, v163, v99
	v_fmac_f32_e32 v186, v167, v99
	v_mul_f32_e32 v26, v92, v154
	v_mul_f32_e32 v27, v93, v154
	v_add_f32_dpp v156, v156, v156 quad_perm:[1,0,3,2] row_mask:0xf bank_mask:0xf bound_ctrl:1
	v_add_f32_dpp v157, v157, v157 quad_perm:[1,0,3,2] row_mask:0xf bank_mask:0xf bound_ctrl:1
	v_mul_f32_e32 v28, v94, v154
	v_mul_f32_e32 v29, v95, v154
	v_mul_f32_e32 v34, v92, v155
	v_mul_f32_e32 v35, v93, v155
	v_add_f32_dpp v156, v156, v156 quad_perm:[2,3,0,1] row_mask:0xf bank_mask:0xf bound_ctrl:1
	v_add_f32_dpp v157, v157, v157 quad_perm:[2,3,0,1] row_mask:0xf bank_mask:0xf bound_ctrl:1
	v_mul_f32_e32 v36, v94, v155
	v_mul_f32_e32 v37, v95, v155
	v_fmac_f32_e32 v26, v160, v80
	v_fmac_f32_e32 v27, v161, v81
	v_add_f32_dpp v156, v156, v156 row_half_mirror row_mask:0xf bank_mask:0xf bound_ctrl:1
	v_add_f32_dpp v157, v157, v157 row_half_mirror row_mask:0xf bank_mask:0xf bound_ctrl:1
	v_fmac_f32_e32 v28, v162, v82
	v_fmac_f32_e32 v29, v163, v83
	v_fmac_f32_e32 v34, v164, v80
	v_fmac_f32_e32 v35, v165, v81
	v_add_f32_dpp v156, v156, v156 row_ror:8 row_mask:0xf bank_mask:0xf bound_ctrl:1
	v_add_f32_dpp v157, v157, v157 row_ror:8 row_mask:0xf bank_mask:0xf bound_ctrl:1
	v_fmac_f32_e32 v36, v166, v82
	v_fmac_f32_e32 v37, v167, v83
	v_fmac_f32_e32 v26, v88, v156
	v_fmac_f32_e32 v34, v88, v157
	v_fmac_f32_e32 v27, v89, v156
	v_fmac_f32_e32 v35, v89, v157
	v_fmac_f32_e32 v28, v90, v156
	v_fmac_f32_e32 v36, v90, v157
	v_fmac_f32_e32 v29, v91, v156
	v_fmac_f32_e32 v37, v91, v157
	ds_read_b128 v[84:87], v0 offset:4288
	ds_read_b64 v[154:155], v62 offset:5312
	ds_read_b128 v[92:95], v0 offset:4800
	ds_read_b128 v[80:83], v0 offset:4032
	ds_read_b128 v[88:91], v0 offset:4544
	ds_read_b128 v[96:99], v0 offset:5056
	s_waitcnt lgkmcnt(6)
	v_mul_f32_e32 v156, v26, v68
	v_mul_f32_e32 v157, v34, v68
	v_mul_f32_e32 v171, v26, v100
	v_mul_f32_e32 v187, v34, v100
	v_fmac_f32_e32 v156, v27, v69
	v_fmac_f32_e32 v157, v35, v69
	v_fmac_f32_e32 v171, v27, v101
	v_fmac_f32_e32 v187, v35, v101
	v_fmac_f32_e32 v156, v28, v70
	v_fmac_f32_e32 v157, v36, v70
	v_fmac_f32_e32 v171, v28, v102
	v_fmac_f32_e32 v187, v36, v102
	v_fmac_f32_e32 v156, v29, v71
	v_fmac_f32_e32 v157, v37, v71
	v_fmac_f32_e32 v171, v29, v103
	v_fmac_f32_e32 v187, v37, v103
	v_mul_f32_e32 v160, v76, v152
	v_mul_f32_e32 v161, v77, v152
	v_add_f32_dpp v156, v156, v156 quad_perm:[1,0,3,2] row_mask:0xf bank_mask:0xf bound_ctrl:1
	v_add_f32_dpp v157, v157, v157 quad_perm:[1,0,3,2] row_mask:0xf bank_mask:0xf bound_ctrl:1
	v_mul_f32_e32 v162, v78, v152
	v_mul_f32_e32 v163, v79, v152
	v_mul_f32_e32 v164, v76, v153
	v_mul_f32_e32 v165, v77, v153
	v_add_f32_dpp v156, v156, v156 quad_perm:[2,3,0,1] row_mask:0xf bank_mask:0xf bound_ctrl:1
	v_add_f32_dpp v157, v157, v157 quad_perm:[2,3,0,1] row_mask:0xf bank_mask:0xf bound_ctrl:1
	v_mul_f32_e32 v166, v78, v153
	v_mul_f32_e32 v167, v79, v153
	v_fmac_f32_e32 v160, v26, v64
	v_fmac_f32_e32 v161, v27, v65
	v_add_f32_dpp v156, v156, v156 row_half_mirror row_mask:0xf bank_mask:0xf bound_ctrl:1
	v_add_f32_dpp v157, v157, v157 row_half_mirror row_mask:0xf bank_mask:0xf bound_ctrl:1
	v_fmac_f32_e32 v162, v28, v66
	v_fmac_f32_e32 v163, v29, v67
	v_fmac_f32_e32 v164, v34, v64
	v_fmac_f32_e32 v165, v35, v65
	v_add_f32_dpp v156, v156, v156 row_ror:8 row_mask:0xf bank_mask:0xf bound_ctrl:1
	v_add_f32_dpp v157, v157, v157 row_ror:8 row_mask:0xf bank_mask:0xf bound_ctrl:1
	v_fmac_f32_e32 v166, v36, v66
	v_fmac_f32_e32 v167, v37, v67
	v_fmac_f32_e32 v160, v72, v156
	v_fmac_f32_e32 v164, v72, v157
	v_fmac_f32_e32 v161, v73, v156
	v_fmac_f32_e32 v165, v73, v157
	v_fmac_f32_e32 v162, v74, v156
	v_fmac_f32_e32 v166, v74, v157
	v_fmac_f32_e32 v163, v75, v156
	v_fmac_f32_e32 v167, v75, v157
	ds_read_b128 v[68:71], v0 offset:5632
	ds_read_b64 v[152:153], v62 offset:6656
	ds_read_b128 v[76:79], v0 offset:6144
	ds_read_b128 v[64:67], v0 offset:5376
	ds_read_b128 v[72:75], v0 offset:5888
	ds_read_b128 v[100:103], v0 offset:6400
	s_waitcnt lgkmcnt(6)
	v_mul_f32_e32 v156, v160, v84
	v_mul_f32_e32 v157, v164, v84
	v_mul_f32_e32 v172, v160, v148
	v_mul_f32_e32 v188, v164, v148
	v_fmac_f32_e32 v156, v161, v85
	v_fmac_f32_e32 v157, v165, v85
	v_fmac_f32_e32 v172, v161, v149
	v_fmac_f32_e32 v188, v165, v149
	v_fmac_f32_e32 v156, v162, v86
	v_fmac_f32_e32 v157, v166, v86
	v_fmac_f32_e32 v172, v162, v150
	v_fmac_f32_e32 v188, v166, v150
	v_fmac_f32_e32 v156, v163, v87
	v_fmac_f32_e32 v157, v167, v87
	v_fmac_f32_e32 v172, v163, v151
	v_fmac_f32_e32 v188, v167, v151
	v_mul_f32_e32 v26, v92, v154
	v_mul_f32_e32 v27, v93, v154
	v_add_f32_dpp v156, v156, v156 quad_perm:[1,0,3,2] row_mask:0xf bank_mask:0xf bound_ctrl:1
	v_add_f32_dpp v157, v157, v157 quad_perm:[1,0,3,2] row_mask:0xf bank_mask:0xf bound_ctrl:1
	v_mul_f32_e32 v28, v94, v154
	v_mul_f32_e32 v29, v95, v154
	v_mul_f32_e32 v34, v92, v155
	v_mul_f32_e32 v35, v93, v155
	v_add_f32_dpp v156, v156, v156 quad_perm:[2,3,0,1] row_mask:0xf bank_mask:0xf bound_ctrl:1
	v_add_f32_dpp v157, v157, v157 quad_perm:[2,3,0,1] row_mask:0xf bank_mask:0xf bound_ctrl:1
	v_mul_f32_e32 v36, v94, v155
	v_mul_f32_e32 v37, v95, v155
	v_fmac_f32_e32 v26, v160, v80
	v_fmac_f32_e32 v27, v161, v81
	v_add_f32_dpp v156, v156, v156 row_half_mirror row_mask:0xf bank_mask:0xf bound_ctrl:1
	v_add_f32_dpp v157, v157, v157 row_half_mirror row_mask:0xf bank_mask:0xf bound_ctrl:1
	v_fmac_f32_e32 v28, v162, v82
	v_fmac_f32_e32 v29, v163, v83
	v_fmac_f32_e32 v34, v164, v80
	v_fmac_f32_e32 v35, v165, v81
	v_add_f32_dpp v156, v156, v156 row_ror:8 row_mask:0xf bank_mask:0xf bound_ctrl:1
	v_add_f32_dpp v157, v157, v157 row_ror:8 row_mask:0xf bank_mask:0xf bound_ctrl:1
	v_fmac_f32_e32 v36, v166, v82
	v_fmac_f32_e32 v37, v167, v83
	v_fmac_f32_e32 v26, v88, v156
	v_fmac_f32_e32 v34, v88, v157
	v_fmac_f32_e32 v27, v89, v156
	v_fmac_f32_e32 v35, v89, v157
	v_fmac_f32_e32 v28, v90, v156
	v_fmac_f32_e32 v36, v90, v157
	v_fmac_f32_e32 v29, v91, v156
	v_fmac_f32_e32 v37, v91, v157
	ds_read_b128 v[84:87], v0 offset:6976
	ds_read_b64 v[154:155], v62 offset:8000
	ds_read_b128 v[92:95], v0 offset:7488
	ds_read_b128 v[80:83], v0 offset:6720
	ds_read_b128 v[88:91], v0 offset:7232
	ds_read_b128 v[148:151], v0 offset:7744
	s_waitcnt lgkmcnt(6)
	v_mul_f32_e32 v156, v26, v68
	v_mul_f32_e32 v157, v34, v68
	v_mul_f32_e32 v173, v26, v96
	v_mul_f32_e32 v189, v34, v96
	v_fmac_f32_e32 v156, v27, v69
	v_fmac_f32_e32 v157, v35, v69
	v_fmac_f32_e32 v173, v27, v97
	v_fmac_f32_e32 v189, v35, v97
	v_fmac_f32_e32 v156, v28, v70
	v_fmac_f32_e32 v157, v36, v70
	v_fmac_f32_e32 v173, v28, v98
	v_fmac_f32_e32 v189, v36, v98
	v_fmac_f32_e32 v156, v29, v71
	v_fmac_f32_e32 v157, v37, v71
	v_fmac_f32_e32 v173, v29, v99
	v_fmac_f32_e32 v189, v37, v99
	v_mul_f32_e32 v160, v76, v152
	v_mul_f32_e32 v161, v77, v152
	v_add_f32_dpp v156, v156, v156 quad_perm:[1,0,3,2] row_mask:0xf bank_mask:0xf bound_ctrl:1
	v_add_f32_dpp v157, v157, v157 quad_perm:[1,0,3,2] row_mask:0xf bank_mask:0xf bound_ctrl:1
	v_mul_f32_e32 v162, v78, v152
	v_mul_f32_e32 v163, v79, v152
	v_mul_f32_e32 v164, v76, v153
	v_mul_f32_e32 v165, v77, v153
	v_add_f32_dpp v156, v156, v156 quad_perm:[2,3,0,1] row_mask:0xf bank_mask:0xf bound_ctrl:1
	v_add_f32_dpp v157, v157, v157 quad_perm:[2,3,0,1] row_mask:0xf bank_mask:0xf bound_ctrl:1
	v_mul_f32_e32 v166, v78, v153
	v_mul_f32_e32 v167, v79, v153
	v_fmac_f32_e32 v160, v26, v64
	v_fmac_f32_e32 v161, v27, v65
	v_add_f32_dpp v156, v156, v156 row_half_mirror row_mask:0xf bank_mask:0xf bound_ctrl:1
	v_add_f32_dpp v157, v157, v157 row_half_mirror row_mask:0xf bank_mask:0xf bound_ctrl:1
	v_fmac_f32_e32 v162, v28, v66
	v_fmac_f32_e32 v163, v29, v67
	v_fmac_f32_e32 v164, v34, v64
	v_fmac_f32_e32 v165, v35, v65
	v_add_f32_dpp v156, v156, v156 row_ror:8 row_mask:0xf bank_mask:0xf bound_ctrl:1
	v_add_f32_dpp v157, v157, v157 row_ror:8 row_mask:0xf bank_mask:0xf bound_ctrl:1
	v_fmac_f32_e32 v166, v36, v66
	v_fmac_f32_e32 v167, v37, v67
	v_fmac_f32_e32 v160, v72, v156
	v_fmac_f32_e32 v164, v72, v157
	v_fmac_f32_e32 v161, v73, v156
	v_fmac_f32_e32 v165, v73, v157
	v_fmac_f32_e32 v162, v74, v156
	v_fmac_f32_e32 v166, v74, v157
	v_fmac_f32_e32 v163, v75, v156
	v_fmac_f32_e32 v167, v75, v157
	ds_read_b128 v[68:71], v0 offset:8320
	ds_read_b64 v[152:153], v62 offset:9344
	ds_read_b128 v[76:79], v0 offset:8832
	ds_read_b128 v[64:67], v0 offset:8064
	ds_read_b128 v[72:75], v0 offset:8576
	ds_read_b128 v[96:99], v0 offset:9088
	s_waitcnt lgkmcnt(6)
	v_mul_f32_e32 v156, v160, v84
	v_mul_f32_e32 v157, v164, v84
	v_mul_f32_e32 v174, v160, v100
	v_mul_f32_e32 v190, v164, v100
	v_fmac_f32_e32 v156, v161, v85
	v_fmac_f32_e32 v157, v165, v85
	v_fmac_f32_e32 v174, v161, v101
	v_fmac_f32_e32 v190, v165, v101
	v_fmac_f32_e32 v156, v162, v86
	v_fmac_f32_e32 v157, v166, v86
	v_fmac_f32_e32 v174, v162, v102
	v_fmac_f32_e32 v190, v166, v102
	v_fmac_f32_e32 v156, v163, v87
	v_fmac_f32_e32 v157, v167, v87
	v_fmac_f32_e32 v174, v163, v103
	v_fmac_f32_e32 v190, v167, v103
	v_mul_f32_e32 v26, v92, v154
	v_mul_f32_e32 v27, v93, v154
	v_add_f32_dpp v156, v156, v156 quad_perm:[1,0,3,2] row_mask:0xf bank_mask:0xf bound_ctrl:1
	v_add_f32_dpp v157, v157, v157 quad_perm:[1,0,3,2] row_mask:0xf bank_mask:0xf bound_ctrl:1
	v_mul_f32_e32 v28, v94, v154
	v_mul_f32_e32 v29, v95, v154
	v_mul_f32_e32 v34, v92, v155
	v_mul_f32_e32 v35, v93, v155
	v_add_f32_dpp v156, v156, v156 quad_perm:[2,3,0,1] row_mask:0xf bank_mask:0xf bound_ctrl:1
	v_add_f32_dpp v157, v157, v157 quad_perm:[2,3,0,1] row_mask:0xf bank_mask:0xf bound_ctrl:1
	v_mul_f32_e32 v36, v94, v155
	v_mul_f32_e32 v37, v95, v155
	v_fmac_f32_e32 v26, v160, v80
	v_fmac_f32_e32 v27, v161, v81
	v_add_f32_dpp v156, v156, v156 row_half_mirror row_mask:0xf bank_mask:0xf bound_ctrl:1
	v_add_f32_dpp v157, v157, v157 row_half_mirror row_mask:0xf bank_mask:0xf bound_ctrl:1
	v_fmac_f32_e32 v28, v162, v82
	v_fmac_f32_e32 v29, v163, v83
	v_fmac_f32_e32 v34, v164, v80
	v_fmac_f32_e32 v35, v165, v81
	v_add_f32_dpp v156, v156, v156 row_ror:8 row_mask:0xf bank_mask:0xf bound_ctrl:1
	v_add_f32_dpp v157, v157, v157 row_ror:8 row_mask:0xf bank_mask:0xf bound_ctrl:1
	v_fmac_f32_e32 v36, v166, v82
	v_fmac_f32_e32 v37, v167, v83
	v_fmac_f32_e32 v26, v88, v156
	v_fmac_f32_e32 v34, v88, v157
	v_fmac_f32_e32 v27, v89, v156
	v_fmac_f32_e32 v35, v89, v157
	v_fmac_f32_e32 v28, v90, v156
	v_fmac_f32_e32 v36, v90, v157
	v_fmac_f32_e32 v29, v91, v156
	v_fmac_f32_e32 v37, v91, v157
	ds_read_b128 v[84:87], v0 offset:9664
	ds_read_b64 v[154:155], v62 offset:10688
	ds_read_b128 v[92:95], v0 offset:10176
	ds_read_b128 v[80:83], v0 offset:9408
	ds_read_b128 v[88:91], v0 offset:9920
	ds_read_b128 v[100:103], v0 offset:10432
	s_waitcnt lgkmcnt(6)
	v_mul_f32_e32 v156, v26, v68
	v_mul_f32_e32 v157, v34, v68
	v_mul_f32_e32 v175, v26, v148
	v_mul_f32_e32 v191, v34, v148
	v_fmac_f32_e32 v156, v27, v69
	v_fmac_f32_e32 v157, v35, v69
	v_fmac_f32_e32 v175, v27, v149
	v_fmac_f32_e32 v191, v35, v149
	v_fmac_f32_e32 v156, v28, v70
	v_fmac_f32_e32 v157, v36, v70
	v_fmac_f32_e32 v175, v28, v150
	v_fmac_f32_e32 v191, v36, v150
	v_fmac_f32_e32 v156, v29, v71
	v_fmac_f32_e32 v157, v37, v71
	v_fmac_f32_e32 v175, v29, v151
	v_fmac_f32_e32 v191, v37, v151
	v_mul_f32_e32 v160, v76, v152
	v_mul_f32_e32 v161, v77, v152
	v_add_f32_dpp v156, v156, v156 quad_perm:[1,0,3,2] row_mask:0xf bank_mask:0xf bound_ctrl:1
	v_add_f32_dpp v157, v157, v157 quad_perm:[1,0,3,2] row_mask:0xf bank_mask:0xf bound_ctrl:1
	v_mul_f32_e32 v162, v78, v152
	v_mul_f32_e32 v163, v79, v152
	v_mul_f32_e32 v164, v76, v153
	v_mul_f32_e32 v165, v77, v153
	v_add_f32_dpp v156, v156, v156 quad_perm:[2,3,0,1] row_mask:0xf bank_mask:0xf bound_ctrl:1
	v_add_f32_dpp v157, v157, v157 quad_perm:[2,3,0,1] row_mask:0xf bank_mask:0xf bound_ctrl:1
	v_mul_f32_e32 v166, v78, v153
	v_mul_f32_e32 v167, v79, v153
	v_fmac_f32_e32 v160, v26, v64
	v_fmac_f32_e32 v161, v27, v65
	v_add_f32_dpp v156, v156, v156 row_half_mirror row_mask:0xf bank_mask:0xf bound_ctrl:1
	v_add_f32_dpp v157, v157, v157 row_half_mirror row_mask:0xf bank_mask:0xf bound_ctrl:1
	v_fmac_f32_e32 v162, v28, v66
	v_fmac_f32_e32 v163, v29, v67
	v_fmac_f32_e32 v164, v34, v64
	v_fmac_f32_e32 v165, v35, v65
	v_add_f32_dpp v156, v156, v156 row_ror:8 row_mask:0xf bank_mask:0xf bound_ctrl:1
	v_add_f32_dpp v157, v157, v157 row_ror:8 row_mask:0xf bank_mask:0xf bound_ctrl:1
	v_fmac_f32_e32 v166, v36, v66
	v_fmac_f32_e32 v167, v37, v67
	v_fmac_f32_e32 v160, v72, v156
	v_fmac_f32_e32 v164, v72, v157
	v_fmac_f32_e32 v161, v73, v156
	v_fmac_f32_e32 v165, v73, v157
	v_fmac_f32_e32 v162, v74, v156
	v_fmac_f32_e32 v166, v74, v157
	v_fmac_f32_e32 v163, v75, v156
	v_fmac_f32_e32 v167, v75, v157
	ds_read_b128 v[68:71], v0 offset:11008
	ds_read_b64 v[152:153], v62 offset:12032
	ds_read_b128 v[76:79], v0 offset:11520
	ds_read_b128 v[64:67], v0 offset:10752
	ds_read_b128 v[72:75], v0 offset:11264
	ds_read_b128 v[148:151], v0 offset:11776
	s_waitcnt lgkmcnt(6)
	v_mul_f32_e32 v156, v160, v84
	v_mul_f32_e32 v157, v164, v84
	v_mul_f32_e32 v176, v160, v96
	v_mul_f32_e32 v192, v164, v96
	v_fmac_f32_e32 v156, v161, v85
	v_fmac_f32_e32 v157, v165, v85
	v_fmac_f32_e32 v176, v161, v97
	v_fmac_f32_e32 v192, v165, v97
	v_fmac_f32_e32 v156, v162, v86
	v_fmac_f32_e32 v157, v166, v86
	v_fmac_f32_e32 v176, v162, v98
	v_fmac_f32_e32 v192, v166, v98
	v_fmac_f32_e32 v156, v163, v87
	v_fmac_f32_e32 v157, v167, v87
	v_fmac_f32_e32 v176, v163, v99
	v_fmac_f32_e32 v192, v167, v99
	v_mul_f32_e32 v26, v92, v154
	v_mul_f32_e32 v27, v93, v154
	v_add_f32_dpp v156, v156, v156 quad_perm:[1,0,3,2] row_mask:0xf bank_mask:0xf bound_ctrl:1
	v_add_f32_dpp v157, v157, v157 quad_perm:[1,0,3,2] row_mask:0xf bank_mask:0xf bound_ctrl:1
	v_mul_f32_e32 v28, v94, v154
	v_mul_f32_e32 v29, v95, v154
	v_mul_f32_e32 v34, v92, v155
	v_mul_f32_e32 v35, v93, v155
	v_add_f32_dpp v156, v156, v156 quad_perm:[2,3,0,1] row_mask:0xf bank_mask:0xf bound_ctrl:1
	v_add_f32_dpp v157, v157, v157 quad_perm:[2,3,0,1] row_mask:0xf bank_mask:0xf bound_ctrl:1
	v_mul_f32_e32 v36, v94, v155
	v_mul_f32_e32 v37, v95, v155
	v_fmac_f32_e32 v26, v160, v80
	v_fmac_f32_e32 v27, v161, v81
	v_add_f32_dpp v156, v156, v156 row_half_mirror row_mask:0xf bank_mask:0xf bound_ctrl:1
	v_add_f32_dpp v157, v157, v157 row_half_mirror row_mask:0xf bank_mask:0xf bound_ctrl:1
	v_fmac_f32_e32 v28, v162, v82
	v_fmac_f32_e32 v29, v163, v83
	v_fmac_f32_e32 v34, v164, v80
	v_fmac_f32_e32 v35, v165, v81
	v_add_f32_dpp v156, v156, v156 row_ror:8 row_mask:0xf bank_mask:0xf bound_ctrl:1
	v_add_f32_dpp v157, v157, v157 row_ror:8 row_mask:0xf bank_mask:0xf bound_ctrl:1
	v_fmac_f32_e32 v36, v166, v82
	v_fmac_f32_e32 v37, v167, v83
	v_fmac_f32_e32 v26, v88, v156
	v_fmac_f32_e32 v34, v88, v157
	v_fmac_f32_e32 v27, v89, v156
	v_fmac_f32_e32 v35, v89, v157
	v_fmac_f32_e32 v28, v90, v156
	v_fmac_f32_e32 v36, v90, v157
	v_fmac_f32_e32 v29, v91, v156
	v_fmac_f32_e32 v37, v91, v157
	ds_read_b128 v[84:87], v0 offset:12352
	ds_read_b64 v[154:155], v62 offset:13376
	ds_read_b128 v[92:95], v0 offset:12864
	ds_read_b128 v[80:83], v0 offset:12096
	ds_read_b128 v[88:91], v0 offset:12608
	ds_read_b128 v[96:99], v0 offset:13120
	s_waitcnt lgkmcnt(6)
	v_mul_f32_e32 v156, v26, v68
	v_mul_f32_e32 v157, v34, v68
	v_mul_f32_e32 v177, v26, v100
	v_mul_f32_e32 v193, v34, v100
	v_fmac_f32_e32 v156, v27, v69
	v_fmac_f32_e32 v157, v35, v69
	v_fmac_f32_e32 v177, v27, v101
	v_fmac_f32_e32 v193, v35, v101
	v_fmac_f32_e32 v156, v28, v70
	v_fmac_f32_e32 v157, v36, v70
	v_fmac_f32_e32 v177, v28, v102
	v_fmac_f32_e32 v193, v36, v102
	v_fmac_f32_e32 v156, v29, v71
	v_fmac_f32_e32 v157, v37, v71
	v_fmac_f32_e32 v177, v29, v103
	v_fmac_f32_e32 v193, v37, v103
	v_mul_f32_e32 v160, v76, v152
	v_mul_f32_e32 v161, v77, v152
	v_add_f32_dpp v156, v156, v156 quad_perm:[1,0,3,2] row_mask:0xf bank_mask:0xf bound_ctrl:1
	v_add_f32_dpp v157, v157, v157 quad_perm:[1,0,3,2] row_mask:0xf bank_mask:0xf bound_ctrl:1
	v_mul_f32_e32 v162, v78, v152
	v_mul_f32_e32 v163, v79, v152
	v_mul_f32_e32 v164, v76, v153
	v_mul_f32_e32 v165, v77, v153
	v_add_f32_dpp v156, v156, v156 quad_perm:[2,3,0,1] row_mask:0xf bank_mask:0xf bound_ctrl:1
	v_add_f32_dpp v157, v157, v157 quad_perm:[2,3,0,1] row_mask:0xf bank_mask:0xf bound_ctrl:1
	v_mul_f32_e32 v166, v78, v153
	v_mul_f32_e32 v167, v79, v153
	v_fmac_f32_e32 v160, v26, v64
	v_fmac_f32_e32 v161, v27, v65
	v_add_f32_dpp v156, v156, v156 row_half_mirror row_mask:0xf bank_mask:0xf bound_ctrl:1
	v_add_f32_dpp v157, v157, v157 row_half_mirror row_mask:0xf bank_mask:0xf bound_ctrl:1
	v_fmac_f32_e32 v162, v28, v66
	v_fmac_f32_e32 v163, v29, v67
	v_fmac_f32_e32 v164, v34, v64
	v_fmac_f32_e32 v165, v35, v65
	v_add_f32_dpp v156, v156, v156 row_ror:8 row_mask:0xf bank_mask:0xf bound_ctrl:1
	v_add_f32_dpp v157, v157, v157 row_ror:8 row_mask:0xf bank_mask:0xf bound_ctrl:1
	v_fmac_f32_e32 v166, v36, v66
	v_fmac_f32_e32 v167, v37, v67
	v_fmac_f32_e32 v160, v72, v156
	v_fmac_f32_e32 v164, v72, v157
	v_fmac_f32_e32 v161, v73, v156
	v_fmac_f32_e32 v165, v73, v157
	v_fmac_f32_e32 v162, v74, v156
	v_fmac_f32_e32 v166, v74, v157
	v_fmac_f32_e32 v163, v75, v156
	v_fmac_f32_e32 v167, v75, v157
	ds_read_b128 v[68:71], v0 offset:13696
	ds_read_b64 v[152:153], v62 offset:14720
	ds_read_b128 v[76:79], v0 offset:14208
	ds_read_b128 v[64:67], v0 offset:13440
	ds_read_b128 v[72:75], v0 offset:13952
	ds_read_b128 v[100:103], v0 offset:14464
	s_waitcnt lgkmcnt(6)
	v_mul_f32_e32 v156, v160, v84
	v_mul_f32_e32 v157, v164, v84
	v_mul_f32_e32 v178, v160, v148
	v_mul_f32_e32 v194, v164, v148
	v_fmac_f32_e32 v156, v161, v85
	v_fmac_f32_e32 v157, v165, v85
	v_fmac_f32_e32 v178, v161, v149
	v_fmac_f32_e32 v194, v165, v149
	v_fmac_f32_e32 v156, v162, v86
	v_fmac_f32_e32 v157, v166, v86
	v_fmac_f32_e32 v178, v162, v150
	v_fmac_f32_e32 v194, v166, v150
	v_fmac_f32_e32 v156, v163, v87
	v_fmac_f32_e32 v157, v167, v87
	v_fmac_f32_e32 v178, v163, v151
	v_fmac_f32_e32 v194, v167, v151
	v_mul_f32_e32 v26, v92, v154
	v_mul_f32_e32 v27, v93, v154
	v_add_f32_dpp v156, v156, v156 quad_perm:[1,0,3,2] row_mask:0xf bank_mask:0xf bound_ctrl:1
	v_add_f32_dpp v157, v157, v157 quad_perm:[1,0,3,2] row_mask:0xf bank_mask:0xf bound_ctrl:1
	v_mul_f32_e32 v28, v94, v154
	v_mul_f32_e32 v29, v95, v154
	v_mul_f32_e32 v34, v92, v155
	v_mul_f32_e32 v35, v93, v155
	v_add_f32_dpp v156, v156, v156 quad_perm:[2,3,0,1] row_mask:0xf bank_mask:0xf bound_ctrl:1
	v_add_f32_dpp v157, v157, v157 quad_perm:[2,3,0,1] row_mask:0xf bank_mask:0xf bound_ctrl:1
	v_mul_f32_e32 v36, v94, v155
	v_mul_f32_e32 v37, v95, v155
	v_fmac_f32_e32 v26, v160, v80
	v_fmac_f32_e32 v27, v161, v81
	v_add_f32_dpp v156, v156, v156 row_half_mirror row_mask:0xf bank_mask:0xf bound_ctrl:1
	v_add_f32_dpp v157, v157, v157 row_half_mirror row_mask:0xf bank_mask:0xf bound_ctrl:1
	v_fmac_f32_e32 v28, v162, v82
	v_fmac_f32_e32 v29, v163, v83
	v_fmac_f32_e32 v34, v164, v80
	v_fmac_f32_e32 v35, v165, v81
	v_add_f32_dpp v156, v156, v156 row_ror:8 row_mask:0xf bank_mask:0xf bound_ctrl:1
	v_add_f32_dpp v157, v157, v157 row_ror:8 row_mask:0xf bank_mask:0xf bound_ctrl:1
	v_fmac_f32_e32 v36, v166, v82
	v_fmac_f32_e32 v37, v167, v83
	v_fmac_f32_e32 v26, v88, v156
	v_fmac_f32_e32 v34, v88, v157
	v_fmac_f32_e32 v27, v89, v156
	v_fmac_f32_e32 v35, v89, v157
	v_fmac_f32_e32 v28, v90, v156
	v_fmac_f32_e32 v36, v90, v157
	v_fmac_f32_e32 v29, v91, v156
	v_fmac_f32_e32 v37, v91, v157
	ds_read_b128 v[84:87], v0 offset:15040
	ds_read_b64 v[154:155], v62 offset:16064
	ds_read_b128 v[92:95], v0 offset:15552
	ds_read_b128 v[80:83], v0 offset:14784
	ds_read_b128 v[88:91], v0 offset:15296
	ds_read_b128 v[148:151], v0 offset:15808
	s_waitcnt lgkmcnt(6)
	v_mul_f32_e32 v156, v26, v68
	v_mul_f32_e32 v157, v34, v68
	v_mul_f32_e32 v179, v26, v96
	v_mul_f32_e32 v195, v34, v96
	v_fmac_f32_e32 v156, v27, v69
	v_fmac_f32_e32 v157, v35, v69
	v_fmac_f32_e32 v179, v27, v97
	v_fmac_f32_e32 v195, v35, v97
	v_fmac_f32_e32 v156, v28, v70
	v_fmac_f32_e32 v157, v36, v70
	v_fmac_f32_e32 v179, v28, v98
	v_fmac_f32_e32 v195, v36, v98
	v_fmac_f32_e32 v156, v29, v71
	v_fmac_f32_e32 v157, v37, v71
	v_fmac_f32_e32 v179, v29, v99
	v_fmac_f32_e32 v195, v37, v99
	v_mul_f32_e32 v160, v76, v152
	v_mul_f32_e32 v161, v77, v152
	v_add_f32_dpp v156, v156, v156 quad_perm:[1,0,3,2] row_mask:0xf bank_mask:0xf bound_ctrl:1
	v_add_f32_dpp v157, v157, v157 quad_perm:[1,0,3,2] row_mask:0xf bank_mask:0xf bound_ctrl:1
	v_mul_f32_e32 v162, v78, v152
	v_mul_f32_e32 v163, v79, v152
	v_mul_f32_e32 v164, v76, v153
	v_mul_f32_e32 v165, v77, v153
	v_add_f32_dpp v156, v156, v156 quad_perm:[2,3,0,1] row_mask:0xf bank_mask:0xf bound_ctrl:1
	v_add_f32_dpp v157, v157, v157 quad_perm:[2,3,0,1] row_mask:0xf bank_mask:0xf bound_ctrl:1
	v_mul_f32_e32 v166, v78, v153
	v_mul_f32_e32 v167, v79, v153
	v_fmac_f32_e32 v160, v26, v64
	v_fmac_f32_e32 v161, v27, v65
	v_add_f32_dpp v156, v156, v156 row_half_mirror row_mask:0xf bank_mask:0xf bound_ctrl:1
	v_add_f32_dpp v157, v157, v157 row_half_mirror row_mask:0xf bank_mask:0xf bound_ctrl:1
	v_fmac_f32_e32 v162, v28, v66
	v_fmac_f32_e32 v163, v29, v67
	v_fmac_f32_e32 v164, v34, v64
	v_fmac_f32_e32 v165, v35, v65
	v_add_f32_dpp v156, v156, v156 row_ror:8 row_mask:0xf bank_mask:0xf bound_ctrl:1
	v_add_f32_dpp v157, v157, v157 row_ror:8 row_mask:0xf bank_mask:0xf bound_ctrl:1
	v_fmac_f32_e32 v166, v36, v66
	v_fmac_f32_e32 v167, v37, v67
	v_fmac_f32_e32 v160, v72, v156
	v_fmac_f32_e32 v164, v72, v157
	v_fmac_f32_e32 v161, v73, v156
	v_fmac_f32_e32 v165, v73, v157
	v_fmac_f32_e32 v162, v74, v156
	v_fmac_f32_e32 v166, v74, v157
	v_fmac_f32_e32 v163, v75, v156
	v_fmac_f32_e32 v167, v75, v157
	ds_read_b128 v[68:71], v0 offset:16384
	ds_read_b64 v[152:153], v62 offset:17408
	ds_read_b128 v[76:79], v0 offset:16896
	ds_read_b128 v[64:67], v0 offset:16128
	ds_read_b128 v[72:75], v0 offset:16640
	ds_read_b128 v[96:99], v0 offset:17152
	s_waitcnt lgkmcnt(6)
	v_mul_f32_e32 v156, v160, v84
	v_mul_f32_e32 v157, v164, v84
	v_mul_f32_e32 v180, v160, v100
	v_mul_f32_e32 v196, v164, v100
	v_fmac_f32_e32 v156, v161, v85
	v_fmac_f32_e32 v157, v165, v85
	v_fmac_f32_e32 v180, v161, v101
	v_fmac_f32_e32 v196, v165, v101
	v_fmac_f32_e32 v156, v162, v86
	v_fmac_f32_e32 v157, v166, v86
	v_fmac_f32_e32 v180, v162, v102
	v_fmac_f32_e32 v196, v166, v102
	v_fmac_f32_e32 v156, v163, v87
	v_fmac_f32_e32 v157, v167, v87
	v_fmac_f32_e32 v180, v163, v103
	v_fmac_f32_e32 v196, v167, v103
	v_mul_f32_e32 v26, v92, v154
	v_mul_f32_e32 v27, v93, v154
	v_add_f32_dpp v156, v156, v156 quad_perm:[1,0,3,2] row_mask:0xf bank_mask:0xf bound_ctrl:1
	v_add_f32_dpp v157, v157, v157 quad_perm:[1,0,3,2] row_mask:0xf bank_mask:0xf bound_ctrl:1
	v_mul_f32_e32 v28, v94, v154
	v_mul_f32_e32 v29, v95, v154
	v_mul_f32_e32 v34, v92, v155
	v_mul_f32_e32 v35, v93, v155
	v_add_f32_dpp v156, v156, v156 quad_perm:[2,3,0,1] row_mask:0xf bank_mask:0xf bound_ctrl:1
	v_add_f32_dpp v157, v157, v157 quad_perm:[2,3,0,1] row_mask:0xf bank_mask:0xf bound_ctrl:1
	v_mul_f32_e32 v36, v94, v155
	v_mul_f32_e32 v37, v95, v155
	v_fmac_f32_e32 v26, v160, v80
	v_fmac_f32_e32 v27, v161, v81
	v_add_f32_dpp v156, v156, v156 row_half_mirror row_mask:0xf bank_mask:0xf bound_ctrl:1
	v_add_f32_dpp v157, v157, v157 row_half_mirror row_mask:0xf bank_mask:0xf bound_ctrl:1
	v_fmac_f32_e32 v28, v162, v82
	v_fmac_f32_e32 v29, v163, v83
	v_fmac_f32_e32 v34, v164, v80
	v_fmac_f32_e32 v35, v165, v81
	v_add_f32_dpp v156, v156, v156 row_ror:8 row_mask:0xf bank_mask:0xf bound_ctrl:1
	v_add_f32_dpp v157, v157, v157 row_ror:8 row_mask:0xf bank_mask:0xf bound_ctrl:1
	v_fmac_f32_e32 v36, v166, v82
	v_fmac_f32_e32 v37, v167, v83
	v_fmac_f32_e32 v26, v88, v156
	v_fmac_f32_e32 v34, v88, v157
	v_fmac_f32_e32 v27, v89, v156
	v_fmac_f32_e32 v35, v89, v157
	v_fmac_f32_e32 v28, v90, v156
	v_fmac_f32_e32 v36, v90, v157
	v_fmac_f32_e32 v29, v91, v156
	v_fmac_f32_e32 v37, v91, v157
	ds_read_b128 v[84:87], v0 offset:17728
	ds_read_b64 v[154:155], v62 offset:18752
	ds_read_b128 v[92:95], v0 offset:18240
	ds_read_b128 v[80:83], v0 offset:17472
	ds_read_b128 v[88:91], v0 offset:17984
	ds_read_b128 v[100:103], v0 offset:18496
	s_waitcnt lgkmcnt(6)
	v_mul_f32_e32 v156, v26, v68
	v_mul_f32_e32 v157, v34, v68
	v_mul_f32_e32 v181, v26, v148
	v_mul_f32_e32 v197, v34, v148
	v_fmac_f32_e32 v156, v27, v69
	v_fmac_f32_e32 v157, v35, v69
	v_fmac_f32_e32 v181, v27, v149
	v_fmac_f32_e32 v197, v35, v149
	v_fmac_f32_e32 v156, v28, v70
	v_fmac_f32_e32 v157, v36, v70
	v_fmac_f32_e32 v181, v28, v150
	v_fmac_f32_e32 v197, v36, v150
	v_fmac_f32_e32 v156, v29, v71
	v_fmac_f32_e32 v157, v37, v71
	v_fmac_f32_e32 v181, v29, v151
	v_fmac_f32_e32 v197, v37, v151
	v_mul_f32_e32 v160, v76, v152
	v_mul_f32_e32 v161, v77, v152
	v_add_f32_dpp v156, v156, v156 quad_perm:[1,0,3,2] row_mask:0xf bank_mask:0xf bound_ctrl:1
	v_add_f32_dpp v157, v157, v157 quad_perm:[1,0,3,2] row_mask:0xf bank_mask:0xf bound_ctrl:1
	v_mul_f32_e32 v162, v78, v152
	v_mul_f32_e32 v163, v79, v152
	v_mul_f32_e32 v164, v76, v153
	v_mul_f32_e32 v165, v77, v153
	v_add_f32_dpp v156, v156, v156 quad_perm:[2,3,0,1] row_mask:0xf bank_mask:0xf bound_ctrl:1
	v_add_f32_dpp v157, v157, v157 quad_perm:[2,3,0,1] row_mask:0xf bank_mask:0xf bound_ctrl:1
	v_mul_f32_e32 v166, v78, v153
	v_mul_f32_e32 v167, v79, v153
	v_fmac_f32_e32 v160, v26, v64
	v_fmac_f32_e32 v161, v27, v65
	v_add_f32_dpp v156, v156, v156 row_half_mirror row_mask:0xf bank_mask:0xf bound_ctrl:1
	v_add_f32_dpp v157, v157, v157 row_half_mirror row_mask:0xf bank_mask:0xf bound_ctrl:1
	v_fmac_f32_e32 v162, v28, v66
	v_fmac_f32_e32 v163, v29, v67
	v_fmac_f32_e32 v164, v34, v64
	v_fmac_f32_e32 v165, v35, v65
	v_add_f32_dpp v156, v156, v156 row_ror:8 row_mask:0xf bank_mask:0xf bound_ctrl:1
	v_add_f32_dpp v157, v157, v157 row_ror:8 row_mask:0xf bank_mask:0xf bound_ctrl:1
	v_fmac_f32_e32 v166, v36, v66
	v_fmac_f32_e32 v167, v37, v67
	v_fmac_f32_e32 v160, v72, v156
	v_fmac_f32_e32 v164, v72, v157
	v_fmac_f32_e32 v161, v73, v156
	v_fmac_f32_e32 v165, v73, v157
	v_fmac_f32_e32 v162, v74, v156
	v_fmac_f32_e32 v166, v74, v157
	v_fmac_f32_e32 v163, v75, v156
	v_fmac_f32_e32 v167, v75, v157
	ds_read_b128 v[68:71], v0 offset:19072
	ds_read_b64 v[152:153], v62 offset:20096
	ds_read_b128 v[76:79], v0 offset:19584
	ds_read_b128 v[64:67], v0 offset:18816
	ds_read_b128 v[72:75], v0 offset:19328
	ds_read_b128 v[148:151], v0 offset:19840
	s_waitcnt lgkmcnt(6)
	v_mul_f32_e32 v156, v160, v84
	v_mul_f32_e32 v157, v164, v84
	v_mul_f32_e32 v182, v160, v96
	v_mul_f32_e32 v198, v164, v96
	v_fmac_f32_e32 v156, v161, v85
	v_fmac_f32_e32 v157, v165, v85
	v_fmac_f32_e32 v182, v161, v97
	v_fmac_f32_e32 v198, v165, v97
	v_fmac_f32_e32 v156, v162, v86
	v_fmac_f32_e32 v157, v166, v86
	v_fmac_f32_e32 v182, v162, v98
	v_fmac_f32_e32 v198, v166, v98
	v_fmac_f32_e32 v156, v163, v87
	v_fmac_f32_e32 v157, v167, v87
	v_fmac_f32_e32 v182, v163, v99
	v_fmac_f32_e32 v198, v167, v99
	v_mul_f32_e32 v26, v92, v154
	v_mul_f32_e32 v27, v93, v154
	v_add_f32_dpp v156, v156, v156 quad_perm:[1,0,3,2] row_mask:0xf bank_mask:0xf bound_ctrl:1
	v_add_f32_dpp v157, v157, v157 quad_perm:[1,0,3,2] row_mask:0xf bank_mask:0xf bound_ctrl:1
	v_mul_f32_e32 v28, v94, v154
	v_mul_f32_e32 v29, v95, v154
	v_mul_f32_e32 v34, v92, v155
	v_mul_f32_e32 v35, v93, v155
	v_add_f32_dpp v156, v156, v156 quad_perm:[2,3,0,1] row_mask:0xf bank_mask:0xf bound_ctrl:1
	v_add_f32_dpp v157, v157, v157 quad_perm:[2,3,0,1] row_mask:0xf bank_mask:0xf bound_ctrl:1
	v_mul_f32_e32 v36, v94, v155
	v_mul_f32_e32 v37, v95, v155
	v_fmac_f32_e32 v26, v160, v80
	v_fmac_f32_e32 v27, v161, v81
	v_add_f32_dpp v156, v156, v156 row_half_mirror row_mask:0xf bank_mask:0xf bound_ctrl:1
	v_add_f32_dpp v157, v157, v157 row_half_mirror row_mask:0xf bank_mask:0xf bound_ctrl:1
	v_fmac_f32_e32 v28, v162, v82
	v_fmac_f32_e32 v29, v163, v83
	v_fmac_f32_e32 v34, v164, v80
	v_fmac_f32_e32 v35, v165, v81
	v_add_f32_dpp v156, v156, v156 row_ror:8 row_mask:0xf bank_mask:0xf bound_ctrl:1
	v_add_f32_dpp v157, v157, v157 row_ror:8 row_mask:0xf bank_mask:0xf bound_ctrl:1
	v_fmac_f32_e32 v36, v166, v82
	v_fmac_f32_e32 v37, v167, v83
	v_fmac_f32_e32 v26, v88, v156
	v_fmac_f32_e32 v34, v88, v157
	v_fmac_f32_e32 v27, v89, v156
	v_fmac_f32_e32 v35, v89, v157
	v_fmac_f32_e32 v28, v90, v156
	v_fmac_f32_e32 v36, v90, v157
	v_fmac_f32_e32 v29, v91, v156
	v_fmac_f32_e32 v37, v91, v157
	ds_read_b128 v[84:87], v0 offset:20416
	ds_read_b64 v[154:155], v62 offset:21440
	ds_read_b128 v[92:95], v0 offset:20928
	ds_read_b128 v[80:83], v0 offset:20160
	ds_read_b128 v[88:91], v0 offset:20672
	ds_read_b128 v[96:99], v0 offset:21184
	s_waitcnt lgkmcnt(6)
	v_mul_f32_e32 v156, v26, v68
	v_mul_f32_e32 v157, v34, v68
	v_mul_f32_e32 v183, v26, v100
	v_mul_f32_e32 v199, v34, v100
	v_fmac_f32_e32 v156, v27, v69
	v_fmac_f32_e32 v157, v35, v69
	v_fmac_f32_e32 v183, v27, v101
	v_fmac_f32_e32 v199, v35, v101
	v_fmac_f32_e32 v156, v28, v70
	v_fmac_f32_e32 v157, v36, v70
	v_fmac_f32_e32 v183, v28, v102
	v_fmac_f32_e32 v199, v36, v102
	v_fmac_f32_e32 v156, v29, v71
	v_fmac_f32_e32 v157, v37, v71
	v_fmac_f32_e32 v183, v29, v103
	v_fmac_f32_e32 v199, v37, v103
	v_mul_f32_e32 v160, v76, v152
	v_mul_f32_e32 v161, v77, v152
	v_add_f32_dpp v156, v156, v156 quad_perm:[1,0,3,2] row_mask:0xf bank_mask:0xf bound_ctrl:1
	v_add_f32_dpp v157, v157, v157 quad_perm:[1,0,3,2] row_mask:0xf bank_mask:0xf bound_ctrl:1
	v_mul_f32_e32 v162, v78, v152
	v_mul_f32_e32 v163, v79, v152
	v_mul_f32_e32 v164, v76, v153
	v_mul_f32_e32 v165, v77, v153
	v_add_f32_dpp v156, v156, v156 quad_perm:[2,3,0,1] row_mask:0xf bank_mask:0xf bound_ctrl:1
	v_add_f32_dpp v157, v157, v157 quad_perm:[2,3,0,1] row_mask:0xf bank_mask:0xf bound_ctrl:1
	v_mul_f32_e32 v166, v78, v153
	v_mul_f32_e32 v167, v79, v153
	v_fmac_f32_e32 v160, v26, v64
	v_fmac_f32_e32 v161, v27, v65
	v_add_f32_dpp v156, v156, v156 row_half_mirror row_mask:0xf bank_mask:0xf bound_ctrl:1
	v_add_f32_dpp v157, v157, v157 row_half_mirror row_mask:0xf bank_mask:0xf bound_ctrl:1
	v_fmac_f32_e32 v162, v28, v66
	v_fmac_f32_e32 v163, v29, v67
	v_fmac_f32_e32 v164, v34, v64
	v_fmac_f32_e32 v165, v35, v65
	v_add_f32_dpp v156, v156, v156 row_ror:8 row_mask:0xf bank_mask:0xf bound_ctrl:1
	v_add_f32_dpp v157, v157, v157 row_ror:8 row_mask:0xf bank_mask:0xf bound_ctrl:1
	v_fmac_f32_e32 v166, v36, v66
	v_fmac_f32_e32 v167, v37, v67
	v_fmac_f32_e32 v160, v72, v156
	v_fmac_f32_e32 v164, v72, v157
	v_fmac_f32_e32 v161, v73, v156
	v_fmac_f32_e32 v165, v73, v157
	v_fmac_f32_e32 v162, v74, v156
	v_fmac_f32_e32 v166, v74, v157
	v_fmac_f32_e32 v163, v75, v156
	v_fmac_f32_e32 v167, v75, v157
	s_waitcnt lgkmcnt(0)
	v_mul_f32_e32 v156, v160, v84
	v_mul_f32_e32 v157, v164, v84
	v_mul_f32_e32 v184, v160, v148
	v_mul_f32_e32 v200, v164, v148
	v_fmac_f32_e32 v156, v161, v85
	v_fmac_f32_e32 v157, v165, v85
	v_fmac_f32_e32 v184, v161, v149
	v_fmac_f32_e32 v200, v165, v149
	v_fmac_f32_e32 v156, v162, v86
	v_fmac_f32_e32 v157, v166, v86
	v_fmac_f32_e32 v184, v162, v150
	v_fmac_f32_e32 v200, v166, v150
	v_fmac_f32_e32 v156, v163, v87
	v_fmac_f32_e32 v157, v167, v87
	v_fmac_f32_e32 v184, v163, v151
	v_fmac_f32_e32 v200, v167, v151
	v_mul_f32_e32 v26, v92, v154
	v_mul_f32_e32 v27, v93, v154
	v_add_f32_dpp v156, v156, v156 quad_perm:[1,0,3,2] row_mask:0xf bank_mask:0xf bound_ctrl:1
	v_add_f32_dpp v157, v157, v157 quad_perm:[1,0,3,2] row_mask:0xf bank_mask:0xf bound_ctrl:1
	v_mul_f32_e32 v28, v94, v154
	v_mul_f32_e32 v29, v95, v154
	v_mul_f32_e32 v34, v92, v155
	v_mul_f32_e32 v35, v93, v155
	v_add_f32_dpp v156, v156, v156 quad_perm:[2,3,0,1] row_mask:0xf bank_mask:0xf bound_ctrl:1
	v_add_f32_dpp v157, v157, v157 quad_perm:[2,3,0,1] row_mask:0xf bank_mask:0xf bound_ctrl:1
	v_mul_f32_e32 v36, v94, v155
	v_mul_f32_e32 v37, v95, v155
	v_fmac_f32_e32 v26, v160, v80
	v_fmac_f32_e32 v27, v161, v81
	v_add_f32_dpp v156, v156, v156 row_half_mirror row_mask:0xf bank_mask:0xf bound_ctrl:1
	v_add_f32_dpp v157, v157, v157 row_half_mirror row_mask:0xf bank_mask:0xf bound_ctrl:1
	v_fmac_f32_e32 v28, v162, v82
	v_fmac_f32_e32 v29, v163, v83
	v_fmac_f32_e32 v34, v164, v80
	v_fmac_f32_e32 v35, v165, v81
	v_add_f32_dpp v156, v156, v156 row_ror:8 row_mask:0xf bank_mask:0xf bound_ctrl:1
	v_add_f32_dpp v157, v157, v157 row_ror:8 row_mask:0xf bank_mask:0xf bound_ctrl:1
	v_fmac_f32_e32 v36, v166, v82
	v_fmac_f32_e32 v37, v167, v83
	v_fmac_f32_e32 v26, v88, v156
	v_fmac_f32_e32 v34, v88, v157
	v_fmac_f32_e32 v27, v89, v156
	v_fmac_f32_e32 v35, v89, v157
	v_fmac_f32_e32 v28, v90, v156
	v_fmac_f32_e32 v36, v90, v157
	v_fmac_f32_e32 v29, v91, v156
	v_fmac_f32_e32 v37, v91, v157
	s_nop 0
	v_mul_f32_e32 v185, v26, v96
	v_mul_f32_e32 v201, v34, v96
	v_mov_b32_e32 v42, v26
	v_mov_b32_e32 v43, v27
	v_fmac_f32_e32 v185, v27, v97
	v_fmac_f32_e32 v201, v35, v97
	v_mov_b32_e32 v44, v28
	v_mov_b32_e32 v45, v29
	v_fmac_f32_e32 v185, v28, v98
	v_fmac_f32_e32 v201, v36, v98
	v_mov_b32_e32 v46, v34
	v_mov_b32_e32 v47, v35
	v_fmac_f32_e32 v185, v29, v99
	v_fmac_f32_e32 v201, v37, v99
	v_mov_b32_e32 v48, v36
	v_mov_b32_e32 v49, v37
	v_mov_b32_e32 v50, v30
	v_mov_b32_e32 v51, v31
	v_mov_b32_e32 v52, v32
	v_mov_b32_e32 v53, v33
	v_mov_b32_e32 v54, v38
	v_mov_b32_e32 v55, v39
	v_mov_b32_e32 v56, v40
	v_mov_b32_e32 v57, v41
	v_add_f32_dpp v170, v170, v170 row_ror:8 row_mask:0xf bank_mask:0xf bound_ctrl:1
	v_add_f32_dpp v186, v186, v186 row_ror:8 row_mask:0xf bank_mask:0xf bound_ctrl:1
	v_add_f32_dpp v171, v171, v171 row_ror:8 row_mask:0xf bank_mask:0xf bound_ctrl:1
	v_add_f32_dpp v187, v187, v187 row_ror:8 row_mask:0xf bank_mask:0xf bound_ctrl:1
	v_add_f32_dpp v172, v172, v172 row_ror:8 row_mask:0xf bank_mask:0xf bound_ctrl:1
	v_add_f32_dpp v188, v188, v188 row_ror:8 row_mask:0xf bank_mask:0xf bound_ctrl:1
	v_add_f32_dpp v173, v173, v173 row_ror:8 row_mask:0xf bank_mask:0xf bound_ctrl:1
	v_add_f32_dpp v189, v189, v189 row_ror:8 row_mask:0xf bank_mask:0xf bound_ctrl:1
	v_add_f32_dpp v174, v174, v174 row_ror:8 row_mask:0xf bank_mask:0xf bound_ctrl:1
	v_add_f32_dpp v190, v190, v190 row_ror:8 row_mask:0xf bank_mask:0xf bound_ctrl:1
	v_add_f32_dpp v175, v175, v175 row_ror:8 row_mask:0xf bank_mask:0xf bound_ctrl:1
	v_add_f32_dpp v191, v191, v191 row_ror:8 row_mask:0xf bank_mask:0xf bound_ctrl:1
	v_add_f32_dpp v176, v176, v176 row_ror:8 row_mask:0xf bank_mask:0xf bound_ctrl:1
	v_add_f32_dpp v192, v192, v192 row_ror:8 row_mask:0xf bank_mask:0xf bound_ctrl:1
	v_add_f32_dpp v177, v177, v177 row_ror:8 row_mask:0xf bank_mask:0xf bound_ctrl:1
	v_add_f32_dpp v193, v193, v193 row_ror:8 row_mask:0xf bank_mask:0xf bound_ctrl:1
	v_add_f32_dpp v170, v178, v178 row_ror:8 row_mask:0xf bank_mask:0xc bound_ctrl:1
	v_add_f32_dpp v186, v194, v194 row_ror:8 row_mask:0xf bank_mask:0xc bound_ctrl:1
	v_add_f32_dpp v171, v179, v179 row_ror:8 row_mask:0xf bank_mask:0xc bound_ctrl:1
	v_add_f32_dpp v187, v195, v195 row_ror:8 row_mask:0xf bank_mask:0xc bound_ctrl:1
	v_add_f32_dpp v172, v180, v180 row_ror:8 row_mask:0xf bank_mask:0xc bound_ctrl:1
	v_add_f32_dpp v188, v196, v196 row_ror:8 row_mask:0xf bank_mask:0xc bound_ctrl:1
	v_add_f32_dpp v173, v181, v181 row_ror:8 row_mask:0xf bank_mask:0xc bound_ctrl:1
	v_add_f32_dpp v189, v197, v197 row_ror:8 row_mask:0xf bank_mask:0xc bound_ctrl:1
	v_add_f32_dpp v174, v182, v182 row_ror:8 row_mask:0xf bank_mask:0xc bound_ctrl:1
	v_add_f32_dpp v190, v198, v198 row_ror:8 row_mask:0xf bank_mask:0xc bound_ctrl:1
	v_add_f32_dpp v175, v183, v183 row_ror:8 row_mask:0xf bank_mask:0xc bound_ctrl:1
	v_add_f32_dpp v191, v199, v199 row_ror:8 row_mask:0xf bank_mask:0xc bound_ctrl:1
	v_add_f32_dpp v176, v184, v184 row_ror:8 row_mask:0xf bank_mask:0xc bound_ctrl:1
	v_add_f32_dpp v192, v200, v200 row_ror:8 row_mask:0xf bank_mask:0xc bound_ctrl:1
	v_add_f32_dpp v177, v185, v185 row_ror:8 row_mask:0xf bank_mask:0xc bound_ctrl:1
	v_add_f32_dpp v193, v201, v201 row_ror:8 row_mask:0xf bank_mask:0xc bound_ctrl:1
	v_add_f32_dpp v170, v170, v170 row_ror:12 row_mask:0xf bank_mask:0x5 bound_ctrl:1
	v_add_f32_dpp v186, v186, v186 row_ror:12 row_mask:0xf bank_mask:0x5 bound_ctrl:1
	v_add_f32_dpp v171, v171, v171 row_ror:12 row_mask:0xf bank_mask:0x5 bound_ctrl:1
	v_add_f32_dpp v187, v187, v187 row_ror:12 row_mask:0xf bank_mask:0x5 bound_ctrl:1
	v_add_f32_dpp v172, v172, v172 row_ror:12 row_mask:0xf bank_mask:0x5 bound_ctrl:1
	v_add_f32_dpp v188, v188, v188 row_ror:12 row_mask:0xf bank_mask:0x5 bound_ctrl:1
	v_add_f32_dpp v173, v173, v173 row_ror:12 row_mask:0xf bank_mask:0x5 bound_ctrl:1
	v_add_f32_dpp v189, v189, v189 row_ror:12 row_mask:0xf bank_mask:0x5 bound_ctrl:1
	v_and_b32_e32 v156, 2, v109
	v_add_f32_dpp v170, v174, v174 row_ror:4 row_mask:0xf bank_mask:0xa bound_ctrl:1
	v_add_f32_dpp v186, v190, v190 row_ror:4 row_mask:0xf bank_mask:0xa bound_ctrl:1
	v_add_f32_dpp v171, v175, v175 row_ror:4 row_mask:0xf bank_mask:0xa bound_ctrl:1
	v_add_f32_dpp v187, v191, v191 row_ror:4 row_mask:0xf bank_mask:0xa bound_ctrl:1
	v_add_f32_dpp v172, v176, v176 row_ror:4 row_mask:0xf bank_mask:0xa bound_ctrl:1
	v_add_f32_dpp v188, v192, v192 row_ror:4 row_mask:0xf bank_mask:0xa bound_ctrl:1
	v_add_f32_dpp v173, v177, v177 row_ror:4 row_mask:0xf bank_mask:0xa bound_ctrl:1
	v_add_f32_dpp v189, v193, v193 row_ror:4 row_mask:0xf bank_mask:0xa bound_ctrl:1
	v_cmp_ne_u32_e32 vcc, 0, v156
	v_ashrrev_i32_e32 v115, 31, v114
	s_nop 0
	v_cndmask_b32_e32 v157, v170, v172, vcc
	v_cndmask_b32_e32 v159, v172, v170, vcc
	v_cndmask_b32_e32 v162, v186, v188, vcc
	v_cndmask_b32_e32 v164, v188, v186, vcc
	v_cndmask_b32_e32 v158, v171, v173, vcc
	v_cndmask_b32_e32 v160, v173, v171, vcc
	v_cndmask_b32_e32 v163, v187, v189, vcc
	v_cndmask_b32_e32 v165, v189, v187, vcc
	v_and_b32_e32 v156, 1, v109
	v_add_f32_dpp v157, v159, v157 quad_perm:[2,3,0,1] row_mask:0xf bank_mask:0xf bound_ctrl:1
	v_add_f32_dpp v162, v164, v162 quad_perm:[2,3,0,1] row_mask:0xf bank_mask:0xf bound_ctrl:1
	v_add_f32_dpp v158, v160, v158 quad_perm:[2,3,0,1] row_mask:0xf bank_mask:0xf bound_ctrl:1
	v_add_f32_dpp v163, v165, v163 quad_perm:[2,3,0,1] row_mask:0xf bank_mask:0xf bound_ctrl:1
	v_cmp_ne_u32_e32 vcc, 0, v156
	s_nop 0
	s_nop 0
	v_cndmask_b32_e32 v159, v158, v157, vcc
	v_cndmask_b32_e32 v164, v163, v162, vcc
	v_cndmask_b32_e32 v160, v157, v158, vcc
	v_cndmask_b32_e32 v165, v162, v163, vcc
	s_nop 0
	v_add_f32_dpp v58, v159, v160 quad_perm:[1,0,3,2] row_mask:0xf bank_mask:0xf bound_ctrl:1
	v_add_f32_dpp v59, v164, v165 quad_perm:[1,0,3,2] row_mask:0xf bank_mask:0xf bound_ctrl:1
	v_lshlrev_b64 v[60:61], 12, v[114:115]
	v_lshl_add_u64 v[60:61], v[112:113], 0, v[60:61]
